# GEMM main loops: all LDS-DMA loads in saddr form (mlp2 included; its split-K state parked in VGPR lanes across the loop) and A-fragment LDS read addresses precomputed once per tile: no VALU besides MF
# speedup vs baseline: 1.0205x; 1.0096x over previous
.LBB0_226:
	s_ashr_i32 s35, s34, 31
	s_lshl_b64 s[6:7], s[34:35], 20
	v_cmp_lt_i64_e32 vcc, s[38:39], v[156:157]
	s_add_u32 s38, s15, s6
	s_addc_u32 s39, s30, s7
	s_and_b64 s[6:7], vcc, exec
	s_cselect_b32 s5, s39, s21
	s_cselect_b32 s6, s38, s20
	s_ashr_i32 s25, s24, 31
	s_lshl_b64 s[42:43], s[24:25], 20
	s_add_u32 s44, s46, s42
	s_addc_u32 s45, s47, s43
	s_and_b64 s[42:43], vcc, exec
	s_cselect_b32 s7, s45, s23
	s_cselect_b32 s25, s44, s22
	s_add_u32 s20, s20, 0x80080
	s_addc_u32 s21, s21, 0
	s_add_u32 s35, s22, 0x100
	v_mov_b32_e32 v0, 0
	s_addc_u32 s57, s23, 0
	s_mov_b32 s58, -2
	v_mov_b32_e32 v1, v0
	v_mov_b32_e32 v2, v0
	v_mov_b32_e32 v3, v0
	v_mov_b32_e32 v4, v0
	v_mov_b32_e32 v5, v0
	v_mov_b32_e32 v6, v0
	v_mov_b32_e32 v7, v0
	v_mov_b32_e32 v12, v0
	v_mov_b32_e32 v13, v0
	v_mov_b32_e32 v14, v0
	v_mov_b32_e32 v15, v0
	v_mov_b32_e32 v20, v0
	v_mov_b32_e32 v21, v0
	v_mov_b32_e32 v22, v0
	v_mov_b32_e32 v23, v0
	v_mov_b32_e32 v28, v0
	v_mov_b32_e32 v29, v0
	v_mov_b32_e32 v30, v0
	v_mov_b32_e32 v31, v0
	v_mov_b32_e32 v36, v0
	v_mov_b32_e32 v37, v0
	v_mov_b32_e32 v38, v0
	v_mov_b32_e32 v39, v0
	v_mov_b32_e32 v44, v0
	v_mov_b32_e32 v45, v0
	v_mov_b32_e32 v46, v0
	v_mov_b32_e32 v47, v0
	v_mov_b32_e32 v52, v0
	v_mov_b32_e32 v53, v0
	v_mov_b32_e32 v54, v0
	v_mov_b32_e32 v55, v0
	v_mov_b32_e32 v8, v0
	v_mov_b32_e32 v9, v0
	v_mov_b32_e32 v10, v0
	v_mov_b32_e32 v11, v0
	v_mov_b32_e32 v16, v0
	v_mov_b32_e32 v17, v0
	v_mov_b32_e32 v18, v0
	v_mov_b32_e32 v19, v0
	v_mov_b32_e32 v24, v0
	v_mov_b32_e32 v25, v0
	v_mov_b32_e32 v26, v0
	v_mov_b32_e32 v27, v0
	v_mov_b32_e32 v32, v0
	v_mov_b32_e32 v33, v0
	v_mov_b32_e32 v34, v0
	v_mov_b32_e32 v35, v0
	v_mov_b32_e32 v40, v0
	v_mov_b32_e32 v41, v0
	v_mov_b32_e32 v42, v0
	v_mov_b32_e32 v43, v0
	v_mov_b32_e32 v48, v0
	v_mov_b32_e32 v49, v0
	v_mov_b32_e32 v50, v0
	v_mov_b32_e32 v51, v0
	v_mov_b32_e32 v56, v0
	v_mov_b32_e32 v57, v0
	v_mov_b32_e32 v58, v0
	v_mov_b32_e32 v59, v0
	v_mov_b32_e32 v60, v0
	v_mov_b32_e32 v61, v0
	v_mov_b32_e32 v62, v0
	v_mov_b32_e32 v63, v0
	v_mov_b32_e32 v64, v0
	v_mov_b32_e32 v65, v0
	v_mov_b32_e32 v66, v0
	v_mov_b32_e32 v67, v0
	v_mov_b32_e32 v68, v0
	v_mov_b32_e32 v69, v0
	v_mov_b32_e32 v70, v0
	v_mov_b32_e32 v71, v0
	v_mov_b32_e32 v80, v0
	v_mov_b32_e32 v81, v0
	v_mov_b32_e32 v82, v0
	v_mov_b32_e32 v83, v0
	v_mov_b32_e32 v84, v0
	v_mov_b32_e32 v85, v0
	v_mov_b32_e32 v86, v0
	v_mov_b32_e32 v87, v0
	v_mov_b32_e32 v96, v0
	v_mov_b32_e32 v97, v0
	v_mov_b32_e32 v98, v0
	v_mov_b32_e32 v99, v0
	v_mov_b32_e32 v100, v0
	v_mov_b32_e32 v101, v0
	v_mov_b32_e32 v102, v0
	v_mov_b32_e32 v103, v0
	v_mov_b32_e32 v112, v0
	v_mov_b32_e32 v113, v0
	v_mov_b32_e32 v114, v0
	v_mov_b32_e32 v115, v0
	v_mov_b32_e32 v116, v0
	v_mov_b32_e32 v117, v0
	v_mov_b32_e32 v118, v0
	v_mov_b32_e32 v119, v0
	v_mov_b32_e32 v72, v0
	v_mov_b32_e32 v73, v0
	v_mov_b32_e32 v74, v0
	v_mov_b32_e32 v75, v0
	v_mov_b32_e32 v76, v0
	v_mov_b32_e32 v77, v0
	v_mov_b32_e32 v78, v0
	v_mov_b32_e32 v79, v0
	v_mov_b32_e32 v88, v0
	v_mov_b32_e32 v89, v0
	v_mov_b32_e32 v90, v0
	v_mov_b32_e32 v91, v0
	v_mov_b32_e32 v92, v0
	v_mov_b32_e32 v93, v0
	v_mov_b32_e32 v94, v0
	v_mov_b32_e32 v95, v0
	v_mov_b32_e32 v104, v0
	v_mov_b32_e32 v105, v0
	v_mov_b32_e32 v106, v0
	v_mov_b32_e32 v107, v0
	v_mov_b32_e32 v108, v0
	v_mov_b32_e32 v109, v0
	v_mov_b32_e32 v110, v0
	v_mov_b32_e32 v111, v0
	v_mov_b32_e32 v120, v0
	v_mov_b32_e32 v121, v0
	v_mov_b32_e32 v122, v0
	v_mov_b32_e32 v123, v0
	v_mov_b32_e32 v124, v0
	v_mov_b32_e32 v125, v0
	v_mov_b32_e32 v126, v0
	v_mov_b32_e32 v127, v0
	v_add_u32_e32 v234, 0x10000, v165
	v_add_u32_e32 v235, 0x14000, v165
	v_add_u32_e32 v236, 0x18000, v165
	v_add_u32_e32 v237, 0x1c000, v165
.LBB0_227:
	s_add_u32 s22, s20, 0xfff80080
	s_addc_u32 s23, s21, -1
	s_add_i32 s59, 0, 0x10000
	ds_read_b128 v[140:143], v234
	ds_read_b128 v[144:147], v234 offset:1024
	ds_read_b128 v[148:151], v234 offset:2048
	ds_read_b128 v[170:173], v234 offset:3072
	s_cmp_eq_u32 s58, 28
	s_cselect_b32 s43, s5, s23
	s_cselect_b32 s42, s6, s22
	s_cselect_b32 s23, s7, s57
	s_cselect_b32 s22, s25, s35
	s_add_i32 m0, s49, 0xc000
	ds_read_b128 v[174:177], v168
	ds_read_b128 v[178:181], v168 offset:1024
	ds_read_b128 v[182:185], v168 offset:2048
	ds_read_b128 v[186:189], v168 offset:3072
	ds_read_b128 v[190:193], v168 offset:4096
	ds_read_b128 v[206:209], v168 offset:5120
	ds_read_b128 v[210:213], v168 offset:6144
	ds_read_b128 v[214:217], v168 offset:7168
	global_load_lds_dwordx4 v136, s[20:21]
	s_add_i32 m0, s49, 0xe000
	s_nop 0
	global_load_lds_dwordx4 v138, s[20:21]
	s_waitcnt lgkmcnt(8)
	s_barrier
	s_waitcnt lgkmcnt(0)
	s_setprio 1
	s_waitcnt lgkmcnt(0)
	v_mfma_f32_16x16x32_bf16 v[124:127], v[140:143], v[174:177], v[124:127]
	v_mfma_f32_16x16x32_bf16 v[120:123], v[148:151], v[174:177], v[120:123]
	v_mfma_f32_16x16x32_bf16 v[108:111], v[140:143], v[182:185], v[108:111]
	v_mfma_f32_16x16x32_bf16 v[104:107], v[148:151], v[182:185], v[104:107]
	v_mfma_f32_16x16x32_bf16 v[92:95], v[140:143], v[190:193], v[92:95]
	v_mfma_f32_16x16x32_bf16 v[88:91], v[148:151], v[190:193], v[88:91]
	v_mfma_f32_16x16x32_bf16 v[76:79], v[140:143], v[210:213], v[76:79]
	v_mfma_f32_16x16x32_bf16 v[72:75], v[148:151], v[210:213], v[72:75]
	v_mfma_f32_16x16x32_bf16 v[124:127], v[144:147], v[178:181], v[124:127]
	v_mfma_f32_16x16x32_bf16 v[120:123], v[170:173], v[178:181], v[120:123]
	v_mfma_f32_16x16x32_bf16 v[108:111], v[144:147], v[186:189], v[108:111]
	v_mfma_f32_16x16x32_bf16 v[104:107], v[170:173], v[186:189], v[104:107]
	v_mfma_f32_16x16x32_bf16 v[92:95], v[144:147], v[206:209], v[92:95]
	v_mfma_f32_16x16x32_bf16 v[88:91], v[170:173], v[206:209], v[88:91]
	v_mfma_f32_16x16x32_bf16 v[76:79], v[144:147], v[214:217], v[76:79]
	v_mfma_f32_16x16x32_bf16 v[72:75], v[170:173], v[214:217], v[72:75]
	s_setprio 0
	s_barrier
	s_add_i32 s62, 0, 0x14000
	s_add_i32 s59, s59, s48
	s_mov_b32 m0, s59
	ds_read_b128 v[218:221], v235
	ds_read_b128 v[222:225], v235 offset:1024
	ds_read_b128 v[226:229], v235 offset:2048
	ds_read_b128 v[230:233], v235 offset:3072
	global_load_lds_dwordx4 v130, s[22:23]
	s_add_i32 m0, s59, 0x2000
	s_nop 0
	global_load_lds_dwordx4 v134, s[22:23]
	s_barrier
	s_waitcnt lgkmcnt(0)
	s_setprio 1
	s_waitcnt lgkmcnt(0)
	v_mfma_f32_16x16x32_bf16 v[116:119], v[218:221], v[174:177], v[116:119]
	v_mfma_f32_16x16x32_bf16 v[112:115], v[226:229], v[174:177], v[112:115]
	v_mfma_f32_16x16x32_bf16 v[100:103], v[218:221], v[182:185], v[100:103]
	v_mfma_f32_16x16x32_bf16 v[96:99], v[226:229], v[182:185], v[96:99]
	v_mfma_f32_16x16x32_bf16 v[84:87], v[218:221], v[190:193], v[84:87]
	v_mfma_f32_16x16x32_bf16 v[80:83], v[226:229], v[190:193], v[80:83]
	v_mfma_f32_16x16x32_bf16 v[68:71], v[218:221], v[210:213], v[68:71]
	v_mfma_f32_16x16x32_bf16 v[64:67], v[226:229], v[210:213], v[64:67]
	v_mfma_f32_16x16x32_bf16 v[116:119], v[222:225], v[178:181], v[116:119]
	v_mfma_f32_16x16x32_bf16 v[112:115], v[230:233], v[178:181], v[112:115]
	v_mfma_f32_16x16x32_bf16 v[100:103], v[222:225], v[186:189], v[100:103]
	v_mfma_f32_16x16x32_bf16 v[96:99], v[230:233], v[186:189], v[96:99]
	v_mfma_f32_16x16x32_bf16 v[84:87], v[222:225], v[206:209], v[84:87]
	v_mfma_f32_16x16x32_bf16 v[80:83], v[230:233], v[206:209], v[80:83]
	v_mfma_f32_16x16x32_bf16 v[68:71], v[222:225], v[214:217], v[68:71]
	v_mfma_f32_16x16x32_bf16 v[64:67], v[230:233], v[214:217], v[64:67]
	s_setprio 0
	s_mov_b32 m0, s49
	s_add_u32 s98, s42, 0x80
	s_addc_u32 s99, s43, 0
	s_barrier
	ds_read_b128 v[174:177], v168 offset:16384
	ds_read_b128 v[178:181], v168 offset:17408
	ds_read_b128 v[182:185], v168 offset:18432
	ds_read_b128 v[186:189], v168 offset:19456
	ds_read_b128 v[190:193], v168 offset:20480
	ds_read_b128 v[206:209], v168 offset:21504
	ds_read_b128 v[210:213], v168 offset:22528
	ds_read_b128 v[214:217], v168 offset:23552
	global_load_lds_dwordx4 v128, s[42:43]
	s_mov_b32 m0, s50
	s_nop 0
	global_load_lds_dwordx4 v132, s[42:43]
	s_barrier
	s_waitcnt lgkmcnt(0)
	s_setprio 1
	s_waitcnt lgkmcnt(0)
	v_mfma_f32_16x16x32_bf16 v[60:63], v[140:143], v[174:177], v[60:63]
	v_mfma_f32_16x16x32_bf16 v[56:59], v[148:151], v[174:177], v[56:59]
	v_mfma_f32_16x16x32_bf16 v[48:51], v[140:143], v[182:185], v[48:51]
	v_mfma_f32_16x16x32_bf16 v[40:43], v[148:151], v[182:185], v[40:43]
	v_mfma_f32_16x16x32_bf16 v[32:35], v[140:143], v[190:193], v[32:35]
	v_mfma_f32_16x16x32_bf16 v[24:27], v[148:151], v[190:193], v[24:27]
	v_mfma_f32_16x16x32_bf16 v[16:19], v[140:143], v[210:213], v[16:19]
	v_mfma_f32_16x16x32_bf16 v[8:11], v[148:151], v[210:213], v[8:11]
	v_mfma_f32_16x16x32_bf16 v[60:63], v[144:147], v[178:181], v[60:63]
	v_mfma_f32_16x16x32_bf16 v[56:59], v[170:173], v[178:181], v[56:59]
	v_mfma_f32_16x16x32_bf16 v[48:51], v[144:147], v[186:189], v[48:51]
	v_mfma_f32_16x16x32_bf16 v[40:43], v[170:173], v[186:189], v[40:43]
	v_mfma_f32_16x16x32_bf16 v[32:35], v[144:147], v[206:209], v[32:35]
	v_mfma_f32_16x16x32_bf16 v[24:27], v[170:173], v[206:209], v[24:27]
	v_mfma_f32_16x16x32_bf16 v[16:19], v[144:147], v[214:217], v[16:19]
	v_mfma_f32_16x16x32_bf16 v[8:11], v[170:173], v[214:217], v[8:11]
	s_setprio 0
	s_barrier
	s_add_u32 s60, s22, 0x80000
	s_addc_u32 s61, s23, 0
	s_add_i32 s59, s62, s48
	s_mov_b32 m0, s59
	s_nop 0
	global_load_lds_dwordx4 v130, s[60:61]
	s_add_i32 m0, s59, 0x2000
	s_nop 0
	global_load_lds_dwordx4 v134, s[60:61]
	s_waitcnt vmcnt(6)
	s_barrier
	s_setprio 1
	v_mfma_f32_16x16x32_bf16 v[52:55], v[218:221], v[174:177], v[52:55]
	v_mfma_f32_16x16x32_bf16 v[44:47], v[226:229], v[174:177], v[44:47]
	v_mfma_f32_16x16x32_bf16 v[36:39], v[218:221], v[182:185], v[36:39]
	v_mfma_f32_16x16x32_bf16 v[28:31], v[226:229], v[182:185], v[28:31]
	v_mfma_f32_16x16x32_bf16 v[20:23], v[218:221], v[190:193], v[20:23]
	v_mfma_f32_16x16x32_bf16 v[12:15], v[226:229], v[190:193], v[12:15]
	v_mfma_f32_16x16x32_bf16 v[4:7], v[218:221], v[210:213], v[4:7]
	v_mfma_f32_16x16x32_bf16 v[0:3], v[226:229], v[210:213], v[0:3]
	v_mfma_f32_16x16x32_bf16 v[52:55], v[222:225], v[178:181], v[52:55]
	v_mfma_f32_16x16x32_bf16 v[44:47], v[230:233], v[178:181], v[44:47]
	v_mfma_f32_16x16x32_bf16 v[36:39], v[222:225], v[186:189], v[36:39]
	v_mfma_f32_16x16x32_bf16 v[28:31], v[230:233], v[186:189], v[28:31]
	v_mfma_f32_16x16x32_bf16 v[20:23], v[222:225], v[206:209], v[20:23]
	v_mfma_f32_16x16x32_bf16 v[12:15], v[230:233], v[206:209], v[12:15]
	v_mfma_f32_16x16x32_bf16 v[4:7], v[222:225], v[214:217], v[4:7]
	v_mfma_f32_16x16x32_bf16 v[0:3], v[230:233], v[214:217], v[0:3]
	s_setprio 0
	s_add_i32 s59, 0, 0x18000
	s_barrier
	ds_read_b128 v[140:143], v236
	ds_read_b128 v[144:147], v236 offset:1024
	ds_read_b128 v[148:151], v236 offset:2048
	ds_read_b128 v[170:173], v236 offset:3072
	s_add_u32 s42, s42, 0x80000
	s_addc_u32 s43, s43, 0
	s_mov_b32 m0, s51
	ds_read_b128 v[174:177], v168 offset:32768
	ds_read_b128 v[178:181], v168 offset:33792
	ds_read_b128 v[182:185], v168 offset:34816
	ds_read_b128 v[186:189], v168 offset:35840
	ds_read_b128 v[190:193], v168 offset:36864
	ds_read_b128 v[206:209], v168 offset:37888
	ds_read_b128 v[210:213], v168 offset:38912
	ds_read_b128 v[214:217], v168 offset:39936
	global_load_lds_dwordx4 v128, s[42:43]
	s_mov_b32 m0, s52
	s_nop 0
	global_load_lds_dwordx4 v132, s[42:43]
	s_waitcnt lgkmcnt(8)
	s_barrier
	s_waitcnt lgkmcnt(0)
	s_setprio 1
	s_waitcnt lgkmcnt(0)
	v_mfma_f32_16x16x32_bf16 v[124:127], v[140:143], v[174:177], v[124:127]
	v_mfma_f32_16x16x32_bf16 v[120:123], v[148:151], v[174:177], v[120:123]
	v_mfma_f32_16x16x32_bf16 v[108:111], v[140:143], v[182:185], v[108:111]
	v_mfma_f32_16x16x32_bf16 v[104:107], v[148:151], v[182:185], v[104:107]
	v_mfma_f32_16x16x32_bf16 v[92:95], v[140:143], v[190:193], v[92:95]
	v_mfma_f32_16x16x32_bf16 v[88:91], v[148:151], v[190:193], v[88:91]
	v_mfma_f32_16x16x32_bf16 v[76:79], v[140:143], v[210:213], v[76:79]
	v_mfma_f32_16x16x32_bf16 v[72:75], v[148:151], v[210:213], v[72:75]
	v_mfma_f32_16x16x32_bf16 v[124:127], v[144:147], v[178:181], v[124:127]
	v_mfma_f32_16x16x32_bf16 v[120:123], v[170:173], v[178:181], v[120:123]
	v_mfma_f32_16x16x32_bf16 v[108:111], v[144:147], v[186:189], v[108:111]
	v_mfma_f32_16x16x32_bf16 v[104:107], v[170:173], v[186:189], v[104:107]
	v_mfma_f32_16x16x32_bf16 v[92:95], v[144:147], v[206:209], v[92:95]
	v_mfma_f32_16x16x32_bf16 v[88:91], v[170:173], v[206:209], v[88:91]
	v_mfma_f32_16x16x32_bf16 v[76:79], v[144:147], v[214:217], v[76:79]
	v_mfma_f32_16x16x32_bf16 v[72:75], v[170:173], v[214:217], v[72:75]
	s_setprio 0
	s_barrier
	s_add_i32 s42, 0, 0x1c000
	s_add_i32 s43, s59, s48
	s_add_u32 s100, s22, 0x80
	s_addc_u32 s101, s23, 0
	s_mov_b32 m0, s43
	ds_read_b128 v[218:221], v237
	ds_read_b128 v[222:225], v237 offset:1024
	ds_read_b128 v[226:229], v237 offset:2048
	ds_read_b128 v[230:233], v237 offset:3072
	global_load_lds_dwordx4 v130, s[100:101]
	s_add_i32 m0, s43, 0x2000
	s_nop 0
	global_load_lds_dwordx4 v134, s[100:101]
	s_barrier
	s_waitcnt lgkmcnt(0)
	s_setprio 1
	s_waitcnt lgkmcnt(0)
	v_mfma_f32_16x16x32_bf16 v[116:119], v[218:221], v[174:177], v[116:119]
	v_mfma_f32_16x16x32_bf16 v[112:115], v[226:229], v[174:177], v[112:115]
	v_mfma_f32_16x16x32_bf16 v[100:103], v[218:221], v[182:185], v[100:103]
	v_mfma_f32_16x16x32_bf16 v[96:99], v[226:229], v[182:185], v[96:99]
	v_mfma_f32_16x16x32_bf16 v[84:87], v[218:221], v[190:193], v[84:87]
	v_mfma_f32_16x16x32_bf16 v[80:83], v[226:229], v[190:193], v[80:83]
	v_mfma_f32_16x16x32_bf16 v[68:71], v[218:221], v[210:213], v[68:71]
	v_mfma_f32_16x16x32_bf16 v[64:67], v[226:229], v[210:213], v[64:67]
	v_mfma_f32_16x16x32_bf16 v[116:119], v[222:225], v[178:181], v[116:119]
	v_mfma_f32_16x16x32_bf16 v[112:115], v[230:233], v[178:181], v[112:115]
	v_mfma_f32_16x16x32_bf16 v[100:103], v[222:225], v[186:189], v[100:103]
	v_mfma_f32_16x16x32_bf16 v[96:99], v[230:233], v[186:189], v[96:99]
	v_mfma_f32_16x16x32_bf16 v[84:87], v[222:225], v[206:209], v[84:87]
	v_mfma_f32_16x16x32_bf16 v[80:83], v[230:233], v[206:209], v[80:83]
	v_mfma_f32_16x16x32_bf16 v[68:71], v[222:225], v[214:217], v[68:71]
	v_mfma_f32_16x16x32_bf16 v[64:67], v[230:233], v[214:217], v[64:67]
	s_setprio 0
	s_mov_b32 m0, s53
	s_barrier
	ds_read_b128 v[174:177], v168 offset:49152
	ds_read_b128 v[178:181], v168 offset:50176
	ds_read_b128 v[182:185], v168 offset:51200
	ds_read_b128 v[186:189], v168 offset:52224
	ds_read_b128 v[190:193], v168 offset:53248
	ds_read_b128 v[206:209], v168 offset:54272
	ds_read_b128 v[210:213], v168 offset:55296
	ds_read_b128 v[214:217], v168 offset:56320
	global_load_lds_dwordx4 v128, s[98:99]
	s_mov_b32 m0, s54
	s_nop 0
	global_load_lds_dwordx4 v132, s[98:99]
	s_barrier
	s_waitcnt lgkmcnt(0)
	s_setprio 1
	s_waitcnt lgkmcnt(0)
	v_mfma_f32_16x16x32_bf16 v[60:63], v[140:143], v[174:177], v[60:63]
	v_mfma_f32_16x16x32_bf16 v[56:59], v[148:151], v[174:177], v[56:59]
	v_mfma_f32_16x16x32_bf16 v[48:51], v[140:143], v[182:185], v[48:51]
	v_mfma_f32_16x16x32_bf16 v[40:43], v[148:151], v[182:185], v[40:43]
	v_mfma_f32_16x16x32_bf16 v[32:35], v[140:143], v[190:193], v[32:35]
	v_mfma_f32_16x16x32_bf16 v[24:27], v[148:151], v[190:193], v[24:27]
	v_mfma_f32_16x16x32_bf16 v[16:19], v[140:143], v[210:213], v[16:19]
	v_mfma_f32_16x16x32_bf16 v[8:11], v[148:151], v[210:213], v[8:11]
	v_mfma_f32_16x16x32_bf16 v[60:63], v[144:147], v[178:181], v[60:63]
	v_mfma_f32_16x16x32_bf16 v[56:59], v[170:173], v[178:181], v[56:59]
	v_mfma_f32_16x16x32_bf16 v[48:51], v[144:147], v[186:189], v[48:51]
	v_mfma_f32_16x16x32_bf16 v[40:43], v[170:173], v[186:189], v[40:43]
	v_mfma_f32_16x16x32_bf16 v[32:35], v[144:147], v[206:209], v[32:35]
	v_mfma_f32_16x16x32_bf16 v[24:27], v[170:173], v[206:209], v[24:27]
	v_mfma_f32_16x16x32_bf16 v[16:19], v[144:147], v[214:217], v[16:19]
	v_mfma_f32_16x16x32_bf16 v[8:11], v[170:173], v[214:217], v[8:11]
	s_setprio 0
	s_barrier
	s_add_u32 s22, s22, 0x80080
	s_addc_u32 s23, s23, 0
	s_add_i32 s42, s42, s48
	s_mov_b32 m0, s42
	s_nop 0
	global_load_lds_dwordx4 v130, s[22:23]
	s_add_i32 m0, s42, 0x2000
	s_nop 0
	global_load_lds_dwordx4 v134, s[22:23]
	s_waitcnt vmcnt(6)
	s_barrier
	s_setprio 1
	v_mfma_f32_16x16x32_bf16 v[52:55], v[218:221], v[174:177], v[52:55]
	v_mfma_f32_16x16x32_bf16 v[44:47], v[226:229], v[174:177], v[44:47]
	v_mfma_f32_16x16x32_bf16 v[36:39], v[218:221], v[182:185], v[36:39]
	v_mfma_f32_16x16x32_bf16 v[28:31], v[226:229], v[182:185], v[28:31]
	v_mfma_f32_16x16x32_bf16 v[20:23], v[218:221], v[190:193], v[20:23]
	v_mfma_f32_16x16x32_bf16 v[12:15], v[226:229], v[190:193], v[12:15]
	v_mfma_f32_16x16x32_bf16 v[4:7], v[218:221], v[210:213], v[4:7]
	v_mfma_f32_16x16x32_bf16 v[0:3], v[226:229], v[210:213], v[0:3]
	v_mfma_f32_16x16x32_bf16 v[52:55], v[222:225], v[178:181], v[52:55]
	v_mfma_f32_16x16x32_bf16 v[44:47], v[230:233], v[178:181], v[44:47]
	v_mfma_f32_16x16x32_bf16 v[36:39], v[222:225], v[186:189], v[36:39]
	v_mfma_f32_16x16x32_bf16 v[28:31], v[230:233], v[186:189], v[28:31]
	v_mfma_f32_16x16x32_bf16 v[20:23], v[222:225], v[206:209], v[20:23]
	v_mfma_f32_16x16x32_bf16 v[12:15], v[230:233], v[206:209], v[12:15]
	v_mfma_f32_16x16x32_bf16 v[4:7], v[222:225], v[214:217], v[4:7]
	v_mfma_f32_16x16x32_bf16 v[0:3], v[230:233], v[214:217], v[0:3]
	s_setprio 0
	s_add_i32 s58, s58, 2
	s_add_u32 s20, s20, 0x100
	s_addc_u32 s21, s21, 0
	s_add_u32 s35, s35, 0x100
	s_addc_u32 s57, s57, 0
	s_cmp_gt_u32 s58, 29
	s_barrier
	s_cbranch_scc0 .LBB0_227
	v_lshl_add_u32 v140, s4, 8, v164
	s_cmp_gt_i32 s56, 23
	s_mov_b64 s[20:21], -1
	s_cbranch_scc1 .LBB0_262
	s_cmp_lt_i32 s56, 4
	s_cselect_b64 s[4:5], -1, 0
	s_and_b32 s6, s56, 0x7ffffffc
	s_cmp_eq_u32 s6, 16
	s_cselect_b64 s[6:7], -1, 0
	s_or_b64 s[20:21], s[4:5], s[6:7]
	s_and_b64 vcc, exec, s[20:21]
	v_mov_b32_e32 v149, v123
	v_mov_b32_e32 v148, v122
	v_mov_b32_e32 v163, v121
	v_mov_b32_e32 v162, v120
	v_mov_b32_e32 v147, v127
	v_mov_b32_e32 v146, v126
	v_mov_b32_e32 v151, v125
	v_mov_b32_e32 v150, v124
	s_cbranch_vccz .LBB0_231
	v_mul_f32_e32 v141, 0xbfb8aa3b, v124
	v_exp_f32_e32 v141, v141
	v_mul_f32_e32 v142, 0xbfb8aa3b, v120
	v_mul_f32_e32 v145, 0xbfb8aa3b, v126
	v_mul_f32_e32 v143, 0xbfb8aa3b, v125
	v_exp_f32_e32 v144, v142
	v_exp_f32_e32 v145, v145
	v_mul_f32_e32 v146, 0xbfb8aa3b, v122
	v_exp_f32_e32 v143, v143
	v_exp_f32_e32 v147, v146
	v_add_f32_e32 v141, 1.0, v141
	v_rcp_f32_e32 v142, v141
	v_add_f32_e32 v141, 1.0, v144
	v_add_f32_e32 v145, 1.0, v145
	v_rcp_f32_e32 v144, v141
	v_add_f32_e32 v141, 1.0, v143
	v_rcp_f32_e32 v146, v145
	v_add_f32_e32 v145, 1.0, v147
	v_mul_f32_e32 v147, 0xbfb8aa3b, v127
	v_rcp_f32_e32 v143, v141
	v_mul_f32_e32 v141, 0xbfb8aa3b, v121
	v_exp_f32_e32 v147, v147
	v_mul_f32_e32 v148, 0xbfb8aa3b, v123
	v_exp_f32_e32 v141, v141
	v_exp_f32_e32 v149, v148
	v_rcp_f32_e32 v148, v145
	v_add_f32_e32 v145, 1.0, v147
	v_add_f32_e32 v141, 1.0, v141
	v_rcp_f32_e32 v147, v145
	v_add_f32_e32 v145, 1.0, v149
	v_rcp_f32_e32 v149, v145
	v_rcp_f32_e32 v145, v141
	v_pk_mul_f32 v[146:147], v[126:127], v[146:147]
	v_pk_mul_f32 v[150:151], v[124:125], v[142:143]
	v_pk_mul_f32 v[148:149], v[122:123], v[148:149]
	v_pk_mul_f32 v[162:163], v[120:121], v[144:145]

.LBB0_560:
	s_ashr_i32 s17, s16, 31
	s_lshl_b64 s[6:7], s[16:17], 20
	v_cmp_lt_i64_e32 vcc, s[24:25], v[160:161]
	s_add_u32 s24, s56, s6
	s_addc_u32 s25, s57, s7
	s_and_b64 s[6:7], vcc, exec
	s_cselect_b32 s5, s25, s23
	s_cselect_b32 s6, s24, s22
	s_ashr_i32 s1, s0, 31
	s_lshl_b64 s[34:35], s[0:1], 20
	s_add_u32 s34, s58, s34
	s_addc_u32 s35, s59, s35
	s_and_b64 s[52:53], vcc, exec
	s_cselect_b32 s1, s35, s39
	s_cselect_b32 s7, s34, s38
	s_add_u32 s22, s22, 0x80080
	s_addc_u32 s23, s23, 0
	s_add_u32 s17, s38, 0x100
	v_mov_b32_e32 v0, 0
	s_addc_u32 s21, s39, 0
	s_mov_b32 s30, -2
	v_mov_b32_e32 v1, v0
	v_mov_b32_e32 v2, v0
	v_mov_b32_e32 v3, v0
	v_mov_b32_e32 v4, v0
	v_mov_b32_e32 v5, v0
	v_mov_b32_e32 v6, v0
	v_mov_b32_e32 v7, v0
	v_mov_b32_e32 v16, v0
	v_mov_b32_e32 v17, v0
	v_mov_b32_e32 v18, v0
	v_mov_b32_e32 v19, v0
	v_mov_b32_e32 v20, v0
	v_mov_b32_e32 v21, v0
	v_mov_b32_e32 v22, v0
	v_mov_b32_e32 v23, v0
	v_mov_b32_e32 v32, v0
	v_mov_b32_e32 v33, v0
	v_mov_b32_e32 v34, v0
	v_mov_b32_e32 v35, v0
	v_mov_b32_e32 v36, v0
	v_mov_b32_e32 v37, v0
	v_mov_b32_e32 v38, v0
	v_mov_b32_e32 v39, v0
	v_mov_b32_e32 v48, v0
	v_mov_b32_e32 v49, v0
	v_mov_b32_e32 v50, v0
	v_mov_b32_e32 v51, v0
	v_mov_b32_e32 v52, v0
	v_mov_b32_e32 v53, v0
	v_mov_b32_e32 v54, v0
	v_mov_b32_e32 v55, v0
	v_mov_b32_e32 v8, v0
	v_mov_b32_e32 v9, v0
	v_mov_b32_e32 v10, v0
	v_mov_b32_e32 v11, v0
	v_mov_b32_e32 v12, v0
	v_mov_b32_e32 v13, v0
	v_mov_b32_e32 v14, v0
	v_mov_b32_e32 v15, v0
	v_mov_b32_e32 v24, v0
	v_mov_b32_e32 v25, v0
	v_mov_b32_e32 v26, v0
	v_mov_b32_e32 v27, v0
	v_mov_b32_e32 v28, v0
	v_mov_b32_e32 v29, v0
	v_mov_b32_e32 v30, v0
	v_mov_b32_e32 v31, v0
	v_mov_b32_e32 v40, v0
	v_mov_b32_e32 v41, v0
	v_mov_b32_e32 v42, v0
	v_mov_b32_e32 v43, v0
	v_mov_b32_e32 v44, v0
	v_mov_b32_e32 v45, v0
	v_mov_b32_e32 v46, v0
	v_mov_b32_e32 v47, v0
	v_mov_b32_e32 v56, v0
	v_mov_b32_e32 v57, v0
	v_mov_b32_e32 v58, v0
	v_mov_b32_e32 v59, v0
	v_mov_b32_e32 v60, v0
	v_mov_b32_e32 v61, v0
	v_mov_b32_e32 v62, v0
	v_mov_b32_e32 v63, v0
	v_mov_b32_e32 v64, v0
	v_mov_b32_e32 v65, v0
	v_mov_b32_e32 v66, v0
	v_mov_b32_e32 v67, v0
	v_mov_b32_e32 v68, v0
	v_mov_b32_e32 v69, v0
	v_mov_b32_e32 v70, v0
	v_mov_b32_e32 v71, v0
	v_mov_b32_e32 v96, v0
	v_mov_b32_e32 v97, v0
	v_mov_b32_e32 v98, v0
	v_mov_b32_e32 v99, v0
	v_mov_b32_e32 v100, v0
	v_mov_b32_e32 v101, v0
	v_mov_b32_e32 v102, v0
	v_mov_b32_e32 v103, v0
	v_mov_b32_e32 v112, v0
	v_mov_b32_e32 v113, v0
	v_mov_b32_e32 v114, v0
	v_mov_b32_e32 v115, v0
	v_mov_b32_e32 v116, v0
	v_mov_b32_e32 v117, v0
	v_mov_b32_e32 v118, v0
	v_mov_b32_e32 v119, v0
	v_mov_b32_e32 v128, v0
	v_mov_b32_e32 v129, v0
	v_mov_b32_e32 v130, v0
	v_mov_b32_e32 v131, v0
	v_mov_b32_e32 v132, v0
	v_mov_b32_e32 v133, v0
	v_mov_b32_e32 v134, v0
	v_mov_b32_e32 v135, v0
	v_mov_b32_e32 v80, v0
	v_mov_b32_e32 v81, v0
	v_mov_b32_e32 v82, v0
	v_mov_b32_e32 v83, v0
	v_mov_b32_e32 v88, v0
	v_mov_b32_e32 v89, v0
	v_mov_b32_e32 v90, v0
	v_mov_b32_e32 v91, v0
	v_mov_b32_e32 v104, v0
	v_mov_b32_e32 v105, v0
	v_mov_b32_e32 v106, v0
	v_mov_b32_e32 v107, v0
	v_mov_b32_e32 v108, v0
	v_mov_b32_e32 v109, v0
	v_mov_b32_e32 v110, v0
	v_mov_b32_e32 v111, v0
	v_mov_b32_e32 v120, v0
	v_mov_b32_e32 v121, v0
	v_mov_b32_e32 v122, v0
	v_mov_b32_e32 v123, v0
	v_mov_b32_e32 v124, v0
	v_mov_b32_e32 v125, v0
	v_mov_b32_e32 v126, v0
	v_mov_b32_e32 v127, v0
	v_mov_b32_e32 v136, v0
	v_mov_b32_e32 v137, v0
	v_mov_b32_e32 v138, v0
	v_mov_b32_e32 v139, v0
	v_mov_b32_e32 v140, v0
	v_mov_b32_e32 v141, v0
	v_mov_b32_e32 v142, v0
	v_mov_b32_e32 v143, v0
	v_add_u32_e32 v246, 0x10000, v206
	v_add_u32_e32 v247, 0x14000, v206
	v_add_u32_e32 v248, 0x18000, v206
	v_add_u32_e32 v249, 0x1c000, v206
.LBB0_561:
	s_add_u32 s38, s22, 0xfff80080
	s_addc_u32 s39, s23, -1
	s_add_i32 s84, 0, 0x10000
	ds_read_b128 v[72:75], v246
	ds_read_b128 v[76:79], v246 offset:1024
	ds_read_b128 v[84:87], v246 offset:2048
	ds_read_b128 v[92:95], v246 offset:3072
	s_cmp_eq_u32 s30, 28
	s_cselect_b32 s53, s5, s39
	s_cselect_b32 s52, s6, s38
	s_cselect_b32 s39, s1, s21
	s_cselect_b32 s38, s7, s17
	s_add_i32 m0, s61, 0xc000
	ds_read_b128 v[144:147], v208
	ds_read_b128 v[148:151], v208 offset:1024
	ds_read_b128 v[188:191], v208 offset:2048
	ds_read_b128 v[210:213], v208 offset:3072
	ds_read_b128 v[214:217], v208 offset:4096
	ds_read_b128 v[218:221], v208 offset:5120
	ds_read_b128 v[222:225], v208 offset:6144
	ds_read_b128 v[226:229], v208 offset:7168
	global_load_lds_dwordx4 v184, s[22:23]
	s_add_i32 m0, s61, 0xe000
	s_nop 0
	global_load_lds_dwordx4 v186, s[22:23]
	s_waitcnt lgkmcnt(8)
	s_barrier
	s_waitcnt lgkmcnt(0)
	s_setprio 1
	s_waitcnt lgkmcnt(0)
	v_mfma_f32_16x16x32_bf16 v[140:143], v[72:75], v[144:147], v[140:143]
	v_mfma_f32_16x16x32_bf16 v[136:139], v[84:87], v[144:147], v[136:139]
	v_mfma_f32_16x16x32_bf16 v[124:127], v[72:75], v[188:191], v[124:127]
	v_mfma_f32_16x16x32_bf16 v[120:123], v[84:87], v[188:191], v[120:123]
	v_mfma_f32_16x16x32_bf16 v[108:111], v[72:75], v[214:217], v[108:111]
	v_mfma_f32_16x16x32_bf16 v[104:107], v[84:87], v[214:217], v[104:107]
	v_mfma_f32_16x16x32_bf16 v[88:91], v[72:75], v[222:225], v[88:91]
	v_mfma_f32_16x16x32_bf16 v[80:83], v[84:87], v[222:225], v[80:83]
	v_mfma_f32_16x16x32_bf16 v[140:143], v[76:79], v[148:151], v[140:143]
	v_mfma_f32_16x16x32_bf16 v[136:139], v[92:95], v[148:151], v[136:139]
	v_mfma_f32_16x16x32_bf16 v[124:127], v[76:79], v[210:213], v[124:127]
	v_mfma_f32_16x16x32_bf16 v[120:123], v[92:95], v[210:213], v[120:123]
	v_mfma_f32_16x16x32_bf16 v[108:111], v[76:79], v[218:221], v[108:111]
	v_mfma_f32_16x16x32_bf16 v[104:107], v[92:95], v[218:221], v[104:107]
	v_mfma_f32_16x16x32_bf16 v[88:91], v[76:79], v[226:229], v[88:91]
	v_mfma_f32_16x16x32_bf16 v[80:83], v[92:95], v[226:229], v[80:83]
	s_setprio 0
	s_barrier
	s_add_i32 s86, 0, 0x14000
	s_add_i32 s84, s84, s60
	ds_read_b128 v[230:233], v247
	ds_read_b128 v[234:237], v247 offset:1024
	ds_read_b128 v[238:241], v247 offset:2048
	ds_read_b128 v[242:245], v247 offset:3072
	s_mov_b32 m0, s84
	s_nop 0
	global_load_lds_dwordx4 v152, s[38:39]
	s_add_i32 m0, s84, 0x2000
	s_nop 0
	global_load_lds_dwordx4 v162, s[38:39]
	s_barrier
	s_waitcnt lgkmcnt(0)
	s_setprio 1
	s_waitcnt lgkmcnt(0)
	v_mfma_f32_16x16x32_bf16 v[132:135], v[230:233], v[144:147], v[132:135]
	v_mfma_f32_16x16x32_bf16 v[128:131], v[238:241], v[144:147], v[128:131]
	v_mfma_f32_16x16x32_bf16 v[116:119], v[230:233], v[188:191], v[116:119]
	v_mfma_f32_16x16x32_bf16 v[112:115], v[238:241], v[188:191], v[112:115]
	v_mfma_f32_16x16x32_bf16 v[100:103], v[230:233], v[214:217], v[100:103]
	v_mfma_f32_16x16x32_bf16 v[96:99], v[238:241], v[214:217], v[96:99]
	v_mfma_f32_16x16x32_bf16 v[68:71], v[230:233], v[222:225], v[68:71]
	v_mfma_f32_16x16x32_bf16 v[64:67], v[238:241], v[222:225], v[64:67]
	v_mfma_f32_16x16x32_bf16 v[132:135], v[234:237], v[148:151], v[132:135]
	v_mfma_f32_16x16x32_bf16 v[128:131], v[242:245], v[148:151], v[128:131]
	v_mfma_f32_16x16x32_bf16 v[116:119], v[234:237], v[210:213], v[116:119]
	v_mfma_f32_16x16x32_bf16 v[112:115], v[242:245], v[210:213], v[112:115]
	v_mfma_f32_16x16x32_bf16 v[100:103], v[234:237], v[218:221], v[100:103]
	v_mfma_f32_16x16x32_bf16 v[96:99], v[242:245], v[218:221], v[96:99]
	v_mfma_f32_16x16x32_bf16 v[68:71], v[234:237], v[226:229], v[68:71]
	v_mfma_f32_16x16x32_bf16 v[64:67], v[242:245], v[226:229], v[64:67]
	s_setprio 0
	s_mov_b32 m0, s61
	s_add_u32 s98, s52, 0x80
	s_addc_u32 s99, s53, 0
	s_barrier
	ds_read_b128 v[144:147], v208 offset:16384
	ds_read_b128 v[148:151], v208 offset:17408
	ds_read_b128 v[188:191], v208 offset:18432
	ds_read_b128 v[210:213], v208 offset:19456
	ds_read_b128 v[214:217], v208 offset:20480
	ds_read_b128 v[218:221], v208 offset:21504
	ds_read_b128 v[222:225], v208 offset:22528
	ds_read_b128 v[226:229], v208 offset:23552
	global_load_lds_dwordx4 v166, s[52:53]
	s_mov_b32 m0, s62
	s_nop 0
	global_load_lds_dwordx4 v164, s[52:53]
	s_barrier
	s_waitcnt lgkmcnt(0)
	s_setprio 1
	s_waitcnt lgkmcnt(0)
	v_mfma_f32_16x16x32_bf16 v[60:63], v[72:75], v[144:147], v[60:63]
	v_mfma_f32_16x16x32_bf16 v[56:59], v[84:87], v[144:147], v[56:59]
	v_mfma_f32_16x16x32_bf16 v[44:47], v[72:75], v[188:191], v[44:47]
	v_mfma_f32_16x16x32_bf16 v[40:43], v[84:87], v[188:191], v[40:43]
	v_mfma_f32_16x16x32_bf16 v[28:31], v[72:75], v[214:217], v[28:31]
	v_mfma_f32_16x16x32_bf16 v[24:27], v[84:87], v[214:217], v[24:27]
	v_mfma_f32_16x16x32_bf16 v[12:15], v[72:75], v[222:225], v[12:15]
	v_mfma_f32_16x16x32_bf16 v[8:11], v[84:87], v[222:225], v[8:11]
	v_mfma_f32_16x16x32_bf16 v[60:63], v[76:79], v[148:151], v[60:63]
	v_mfma_f32_16x16x32_bf16 v[56:59], v[92:95], v[148:151], v[56:59]
	v_mfma_f32_16x16x32_bf16 v[44:47], v[76:79], v[210:213], v[44:47]
	v_mfma_f32_16x16x32_bf16 v[40:43], v[92:95], v[210:213], v[40:43]
	v_mfma_f32_16x16x32_bf16 v[28:31], v[76:79], v[218:221], v[28:31]
	v_mfma_f32_16x16x32_bf16 v[24:27], v[92:95], v[218:221], v[24:27]
	v_mfma_f32_16x16x32_bf16 v[12:15], v[76:79], v[226:229], v[12:15]
	v_mfma_f32_16x16x32_bf16 v[8:11], v[92:95], v[226:229], v[8:11]
	s_setprio 0
	s_barrier
	s_add_u32 s84, s38, 0x80000
	s_addc_u32 s85, s39, 0
	s_add_i32 s86, s86, s60
	s_mov_b32 m0, s86
	s_nop 0
	global_load_lds_dwordx4 v152, s[84:85]
	s_add_i32 m0, s86, 0x2000
	s_nop 0
	global_load_lds_dwordx4 v162, s[84:85]
	s_waitcnt vmcnt(6)
	s_barrier
	s_setprio 1
	v_mfma_f32_16x16x32_bf16 v[52:55], v[230:233], v[144:147], v[52:55]
	v_mfma_f32_16x16x32_bf16 v[48:51], v[238:241], v[144:147], v[48:51]
	v_mfma_f32_16x16x32_bf16 v[36:39], v[230:233], v[188:191], v[36:39]
	v_mfma_f32_16x16x32_bf16 v[32:35], v[238:241], v[188:191], v[32:35]
	v_mfma_f32_16x16x32_bf16 v[20:23], v[230:233], v[214:217], v[20:23]
	v_mfma_f32_16x16x32_bf16 v[16:19], v[238:241], v[214:217], v[16:19]
	v_mfma_f32_16x16x32_bf16 v[4:7], v[230:233], v[222:225], v[4:7]
	v_mfma_f32_16x16x32_bf16 v[0:3], v[238:241], v[222:225], v[0:3]
	v_mfma_f32_16x16x32_bf16 v[52:55], v[234:237], v[148:151], v[52:55]
	v_mfma_f32_16x16x32_bf16 v[48:51], v[242:245], v[148:151], v[48:51]
	v_mfma_f32_16x16x32_bf16 v[36:39], v[234:237], v[210:213], v[36:39]
	v_mfma_f32_16x16x32_bf16 v[32:35], v[242:245], v[210:213], v[32:35]
	v_mfma_f32_16x16x32_bf16 v[20:23], v[234:237], v[218:221], v[20:23]
	v_mfma_f32_16x16x32_bf16 v[16:19], v[242:245], v[218:221], v[16:19]
	v_mfma_f32_16x16x32_bf16 v[4:7], v[234:237], v[226:229], v[4:7]
	v_mfma_f32_16x16x32_bf16 v[0:3], v[242:245], v[226:229], v[0:3]
	s_setprio 0
	s_add_i32 s84, 0, 0x18000
	s_barrier
	ds_read_b128 v[72:75], v248
	ds_read_b128 v[76:79], v248 offset:1024
	ds_read_b128 v[84:87], v248 offset:2048
	ds_read_b128 v[92:95], v248 offset:3072
	s_add_u32 s52, s52, 0x80000
	s_addc_u32 s53, s53, 0
	s_mov_b32 m0, s63
	ds_read_b128 v[144:147], v208 offset:32768
	ds_read_b128 v[148:151], v208 offset:33792
	ds_read_b128 v[188:191], v208 offset:34816
	ds_read_b128 v[210:213], v208 offset:35840
	ds_read_b128 v[214:217], v208 offset:36864
	ds_read_b128 v[218:221], v208 offset:37888
	ds_read_b128 v[222:225], v208 offset:38912
	ds_read_b128 v[226:229], v208 offset:39936
	global_load_lds_dwordx4 v166, s[52:53]
	s_mov_b32 m0, s68
	s_nop 0
	global_load_lds_dwordx4 v164, s[52:53]
	s_waitcnt lgkmcnt(8)
	s_barrier
	s_waitcnt lgkmcnt(0)
	s_setprio 1
	s_waitcnt lgkmcnt(0)
	v_mfma_f32_16x16x32_bf16 v[140:143], v[72:75], v[144:147], v[140:143]
	v_mfma_f32_16x16x32_bf16 v[136:139], v[84:87], v[144:147], v[136:139]
	v_mfma_f32_16x16x32_bf16 v[124:127], v[72:75], v[188:191], v[124:127]
	v_mfma_f32_16x16x32_bf16 v[120:123], v[84:87], v[188:191], v[120:123]
	v_mfma_f32_16x16x32_bf16 v[108:111], v[72:75], v[214:217], v[108:111]
	v_mfma_f32_16x16x32_bf16 v[104:107], v[84:87], v[214:217], v[104:107]
	v_mfma_f32_16x16x32_bf16 v[88:91], v[72:75], v[222:225], v[88:91]
	v_mfma_f32_16x16x32_bf16 v[80:83], v[84:87], v[222:225], v[80:83]
	v_mfma_f32_16x16x32_bf16 v[140:143], v[76:79], v[148:151], v[140:143]
	v_mfma_f32_16x16x32_bf16 v[136:139], v[92:95], v[148:151], v[136:139]
	v_mfma_f32_16x16x32_bf16 v[124:127], v[76:79], v[210:213], v[124:127]
	v_mfma_f32_16x16x32_bf16 v[120:123], v[92:95], v[210:213], v[120:123]
	v_mfma_f32_16x16x32_bf16 v[108:111], v[76:79], v[218:221], v[108:111]
	v_mfma_f32_16x16x32_bf16 v[104:107], v[92:95], v[218:221], v[104:107]
	v_mfma_f32_16x16x32_bf16 v[88:91], v[76:79], v[226:229], v[88:91]
	v_mfma_f32_16x16x32_bf16 v[80:83], v[92:95], v[226:229], v[80:83]
	s_setprio 0
	s_barrier
	s_add_i32 s52, 0, 0x1c000
	s_add_i32 s53, s84, s60
	s_add_u32 s100, s38, 0x80
	s_addc_u32 s101, s39, 0
	s_mov_b32 m0, s53
	ds_read_b128 v[230:233], v249
	ds_read_b128 v[234:237], v249 offset:1024
	ds_read_b128 v[238:241], v249 offset:2048
	ds_read_b128 v[242:245], v249 offset:3072
	global_load_lds_dwordx4 v152, s[100:101]
	s_add_i32 m0, s53, 0x2000
	s_nop 0
	global_load_lds_dwordx4 v162, s[100:101]
	s_barrier
	s_waitcnt lgkmcnt(0)
	s_setprio 1
	s_waitcnt lgkmcnt(0)
	v_mfma_f32_16x16x32_bf16 v[132:135], v[230:233], v[144:147], v[132:135]
	v_mfma_f32_16x16x32_bf16 v[128:131], v[238:241], v[144:147], v[128:131]
	v_mfma_f32_16x16x32_bf16 v[116:119], v[230:233], v[188:191], v[116:119]
	v_mfma_f32_16x16x32_bf16 v[112:115], v[238:241], v[188:191], v[112:115]
	v_mfma_f32_16x16x32_bf16 v[100:103], v[230:233], v[214:217], v[100:103]
	v_mfma_f32_16x16x32_bf16 v[96:99], v[238:241], v[214:217], v[96:99]
	v_mfma_f32_16x16x32_bf16 v[68:71], v[230:233], v[222:225], v[68:71]
	v_mfma_f32_16x16x32_bf16 v[64:67], v[238:241], v[222:225], v[64:67]
	v_mfma_f32_16x16x32_bf16 v[132:135], v[234:237], v[148:151], v[132:135]
	v_mfma_f32_16x16x32_bf16 v[128:131], v[242:245], v[148:151], v[128:131]
	v_mfma_f32_16x16x32_bf16 v[116:119], v[234:237], v[210:213], v[116:119]
	v_mfma_f32_16x16x32_bf16 v[112:115], v[242:245], v[210:213], v[112:115]
	v_mfma_f32_16x16x32_bf16 v[100:103], v[234:237], v[218:221], v[100:103]
	v_mfma_f32_16x16x32_bf16 v[96:99], v[242:245], v[218:221], v[96:99]
	v_mfma_f32_16x16x32_bf16 v[68:71], v[234:237], v[226:229], v[68:71]
	v_mfma_f32_16x16x32_bf16 v[64:67], v[242:245], v[226:229], v[64:67]
	s_setprio 0
	s_mov_b32 m0, s81
	s_barrier
	ds_read_b128 v[144:147], v208 offset:49152
	ds_read_b128 v[148:151], v208 offset:50176
	ds_read_b128 v[188:191], v208 offset:51200
	ds_read_b128 v[210:213], v208 offset:52224
	ds_read_b128 v[214:217], v208 offset:53248
	ds_read_b128 v[218:221], v208 offset:54272
	ds_read_b128 v[222:225], v208 offset:55296
	ds_read_b128 v[226:229], v208 offset:56320
	global_load_lds_dwordx4 v166, s[98:99]
	s_mov_b32 m0, s82
	s_nop 0
	global_load_lds_dwordx4 v164, s[98:99]
	s_barrier
	s_waitcnt lgkmcnt(0)
	s_setprio 1
	s_waitcnt lgkmcnt(0)
	v_mfma_f32_16x16x32_bf16 v[60:63], v[72:75], v[144:147], v[60:63]
	v_mfma_f32_16x16x32_bf16 v[56:59], v[84:87], v[144:147], v[56:59]
	v_mfma_f32_16x16x32_bf16 v[44:47], v[72:75], v[188:191], v[44:47]
	v_mfma_f32_16x16x32_bf16 v[40:43], v[84:87], v[188:191], v[40:43]
	v_mfma_f32_16x16x32_bf16 v[28:31], v[72:75], v[214:217], v[28:31]
	v_mfma_f32_16x16x32_bf16 v[24:27], v[84:87], v[214:217], v[24:27]
	v_mfma_f32_16x16x32_bf16 v[12:15], v[72:75], v[222:225], v[12:15]
	v_mfma_f32_16x16x32_bf16 v[8:11], v[84:87], v[222:225], v[8:11]
	v_mfma_f32_16x16x32_bf16 v[60:63], v[76:79], v[148:151], v[60:63]
	v_mfma_f32_16x16x32_bf16 v[56:59], v[92:95], v[148:151], v[56:59]
	v_mfma_f32_16x16x32_bf16 v[44:47], v[76:79], v[210:213], v[44:47]
	v_mfma_f32_16x16x32_bf16 v[40:43], v[92:95], v[210:213], v[40:43]
	v_mfma_f32_16x16x32_bf16 v[28:31], v[76:79], v[218:221], v[28:31]
	v_mfma_f32_16x16x32_bf16 v[24:27], v[92:95], v[218:221], v[24:27]
	v_mfma_f32_16x16x32_bf16 v[12:15], v[76:79], v[226:229], v[12:15]
	v_mfma_f32_16x16x32_bf16 v[8:11], v[92:95], v[226:229], v[8:11]
	s_setprio 0
	s_barrier
	s_add_u32 s38, s38, 0x80080
	s_addc_u32 s39, s39, 0
	s_add_i32 s52, s52, s60
	s_mov_b32 m0, s52
	s_nop 0
	global_load_lds_dwordx4 v152, s[38:39]
	s_add_i32 m0, s52, 0x2000
	s_nop 0
	global_load_lds_dwordx4 v162, s[38:39]
	s_waitcnt vmcnt(6)
	s_barrier
	s_setprio 1
	v_mfma_f32_16x16x32_bf16 v[52:55], v[230:233], v[144:147], v[52:55]
	v_mfma_f32_16x16x32_bf16 v[48:51], v[238:241], v[144:147], v[48:51]
	v_mfma_f32_16x16x32_bf16 v[36:39], v[230:233], v[188:191], v[36:39]
	v_mfma_f32_16x16x32_bf16 v[32:35], v[238:241], v[188:191], v[32:35]
	v_mfma_f32_16x16x32_bf16 v[20:23], v[230:233], v[214:217], v[20:23]
	v_mfma_f32_16x16x32_bf16 v[16:19], v[238:241], v[214:217], v[16:19]
	v_mfma_f32_16x16x32_bf16 v[4:7], v[230:233], v[222:225], v[4:7]
	v_mfma_f32_16x16x32_bf16 v[0:3], v[238:241], v[222:225], v[0:3]
	v_mfma_f32_16x16x32_bf16 v[52:55], v[234:237], v[148:151], v[52:55]
	v_mfma_f32_16x16x32_bf16 v[48:51], v[242:245], v[148:151], v[48:51]
	v_mfma_f32_16x16x32_bf16 v[36:39], v[234:237], v[210:213], v[36:39]
	v_mfma_f32_16x16x32_bf16 v[32:35], v[242:245], v[210:213], v[32:35]
	v_mfma_f32_16x16x32_bf16 v[20:23], v[234:237], v[218:221], v[20:23]
	v_mfma_f32_16x16x32_bf16 v[16:19], v[242:245], v[218:221], v[16:19]
	v_mfma_f32_16x16x32_bf16 v[4:7], v[234:237], v[226:229], v[4:7]
	v_mfma_f32_16x16x32_bf16 v[0:3], v[242:245], v[226:229], v[0:3]
	s_setprio 0
	s_add_i32 s30, s30, 2
	s_add_u32 s22, s22, 0x100
	s_addc_u32 s23, s23, 0
	s_add_u32 s17, s17, 0x100
	s_addc_u32 s21, s21, 0
	s_cmp_gt_u32 s30, 29
	s_barrier
	s_cbranch_scc0 .LBB0_561
	v_lshl_or_b32 v188, s4, 8, v207
	v_ashrrev_i32_e32 v189, 31, v188
	s_cmp_lt_i32 s20, 16
	s_cselect_b32 s6, s44, s46
	s_cselect_b32 s7, s45, s47
	s_cselect_b32 s1, 0, 16
	s_sub_i32 s4, s20, s1
	s_mov_b32 s5, 0
	s_lshl_b64 s[4:5], s[4:5], 21
	s_add_u32 s38, s6, s4
	s_addc_u32 s39, s7, s5
	s_cmp_lt_i32 s20, 32
	s_cselect_b32 s1, 0x3000, s73
	s_cmp_lt_i32 s20, 16
	s_cselect_b32 s1, 0, s1
	s_lshl_b32 s1, s1, 2
	s_add_u32 s6, s79, s1
	s_addc_u32 s7, s80, 0
	s_mov_b32 s4, s20
	s_mov_b32 s5, 0
	s_lshl_b64 s[4:5], s[4:5], 20
	s_add_u32 s52, s69, s4
	s_addc_u32 s53, s78, s5
	v_lshl_add_u64 v[190:191], v[188:189], 2, s[6:7]
	s_mov_b64 s[4:5], 0x28504000
	v_lshl_add_u64 v[190:191], v[190:191], 0, s[4:5]
	global_load_dwordx4 v[92:95], v[190:191], off
	global_load_dwordx4 v[84:87], v[190:191], off offset:16
	global_load_dwordx4 v[76:79], v[190:191], off offset:512
	global_load_dwordx4 v[72:75], v[190:191], off offset:528
	v_lshl_add_u64 v[144:145], v[188:189], 1, s[52:53]
	s_and_b64 vcc, exec, s[64:65]
	s_cbranch_vccz .Lwo_epi_f32
	v_lshl_add_u64 v[148:149], v[168:169], 1, v[144:145]
	global_load_dwordx4 v[210:213], v[148:149], off
	global_load_dwordx4 v[214:217], v[148:149], off offset:256
	v_lshl_add_u64 v[148:149], v[170:171], 1, v[144:145]
	global_load_dwordx4 v[218:221], v[148:149], off
	global_load_dwordx4 v[222:225], v[148:149], off offset:256
	v_lshl_add_u64 v[148:149], v[172:173], 1, v[144:145]
	global_load_dwordx4 v[226:229], v[148:149], off
	global_load_dwordx4 v[230:233], v[148:149], off offset:256
	v_lshl_add_u64 v[148:149], v[174:175], 1, v[144:145]
	global_load_dwordx4 v[234:237], v[148:149], off
	global_load_dwordx4 v[238:241], v[148:149], off offset:256
	v_lshl_add_u64 v[148:149], v[176:177], 1, v[144:145]
	global_load_dwordx4 v[242:245], v[148:149], off
	s_waitcnt vmcnt(8)
	v_lshlrev_b32_e32 v188, 16, v210
	v_and_b32_e32 v189, 0xffff0000, v210
	v_lshlrev_b32_e32 v190, 16, v211
	v_and_b32_e32 v191, 0xffff0000, v211
	v_lshlrev_b32_e32 v246, 16, v212
	v_and_b32_e32 v247, 0xffff0000, v212
	v_lshlrev_b32_e32 v248, 16, v213
	v_and_b32_e32 v249, 0xffff0000, v213
	global_load_dwordx4 v[210:213], v[148:149], off offset:256
	v_lshl_add_u64 v[150:151], v[168:169], 1, v[144:145]
	v_pk_fma_f32 v[140:141], v[140:141], v[92:93], v[188:189]
	v_pk_fma_f32 v[142:143], v[142:143], v[94:95], v[190:191]
	v_pk_fma_f32 v[136:137], v[136:137], v[84:85], v[246:247]
	v_pk_fma_f32 v[138:139], v[138:139], v[86:87], v[248:249]
	v_cvt_pk_bf16_f32 v140, v140, v141
	v_cvt_pk_bf16_f32 v141, v142, v143
	v_cvt_pk_bf16_f32 v142, v136, v137
	v_cvt_pk_bf16_f32 v143, v138, v139
	global_store_dwordx4 v[150:151], v[140:143], off
	s_waitcnt vmcnt(9)
	v_lshlrev_b32_e32 v188, 16, v214
	v_and_b32_e32 v189, 0xffff0000, v214
	v_lshlrev_b32_e32 v190, 16, v215
	v_and_b32_e32 v191, 0xffff0000, v215
	v_lshlrev_b32_e32 v246, 16, v216
	v_and_b32_e32 v247, 0xffff0000, v216
	v_lshlrev_b32_e32 v248, 16, v217
	v_and_b32_e32 v249, 0xffff0000, v217
	v_lshl_add_u64 v[148:149], v[178:179], 1, v[144:145]
	global_load_dwordx4 v[214:217], v[148:149], off
	v_pk_fma_f32 v[132:133], v[132:133], v[76:77], v[188:189]
	v_pk_fma_f32 v[134:135], v[134:135], v[78:79], v[190:191]
	v_pk_fma_f32 v[128:129], v[128:129], v[72:73], v[246:247]
	v_pk_fma_f32 v[130:131], v[130:131], v[74:75], v[248:249]
	v_cvt_pk_bf16_f32 v132, v132, v133
	v_cvt_pk_bf16_f32 v133, v134, v135
	v_cvt_pk_bf16_f32 v134, v128, v129
	v_cvt_pk_bf16_f32 v135, v130, v131
	global_store_dwordx4 v[150:151], v[132:135], off offset:256
	s_waitcnt vmcnt(10)
	v_lshlrev_b32_e32 v188, 16, v218
	v_and_b32_e32 v189, 0xffff0000, v218
	v_lshlrev_b32_e32 v190, 16, v219
	v_and_b32_e32 v191, 0xffff0000, v219
	v_lshlrev_b32_e32 v246, 16, v220
	v_and_b32_e32 v247, 0xffff0000, v220
	v_lshlrev_b32_e32 v248, 16, v221
	v_and_b32_e32 v249, 0xffff0000, v221
	global_load_dwordx4 v[218:221], v[148:149], off offset:256
	v_lshl_add_u64 v[192:193], v[170:171], 1, v[144:145]
	v_pk_fma_f32 v[124:125], v[124:125], v[92:93], v[188:189]
	v_pk_fma_f32 v[126:127], v[126:127], v[94:95], v[190:191]
	v_pk_fma_f32 v[120:121], v[120:121], v[84:85], v[246:247]
	v_pk_fma_f32 v[122:123], v[122:123], v[86:87], v[248:249]
	v_cvt_pk_bf16_f32 v124, v124, v125
	v_cvt_pk_bf16_f32 v125, v126, v127
	v_cvt_pk_bf16_f32 v126, v120, v121
	v_cvt_pk_bf16_f32 v127, v122, v123
	global_store_dwordx4 v[192:193], v[124:127], off
	s_waitcnt vmcnt(11)
	v_lshlrev_b32_e32 v188, 16, v222
	v_and_b32_e32 v189, 0xffff0000, v222
	v_lshlrev_b32_e32 v190, 16, v223
	v_and_b32_e32 v191, 0xffff0000, v223
	v_lshlrev_b32_e32 v246, 16, v224
	v_and_b32_e32 v247, 0xffff0000, v224
	v_lshlrev_b32_e32 v248, 16, v225
	v_and_b32_e32 v249, 0xffff0000, v225
	v_lshl_add_u64 v[148:149], v[180:181], 1, v[144:145]
	global_load_dwordx4 v[222:225], v[148:149], off
	v_pk_fma_f32 v[116:117], v[116:117], v[76:77], v[188:189]
	v_pk_fma_f32 v[118:119], v[118:119], v[78:79], v[190:191]
	v_pk_fma_f32 v[112:113], v[112:113], v[72:73], v[246:247]
	v_pk_fma_f32 v[114:115], v[114:115], v[74:75], v[248:249]
	v_cvt_pk_bf16_f32 v116, v116, v117
	v_cvt_pk_bf16_f32 v117, v118, v119
	v_cvt_pk_bf16_f32 v118, v112, v113
	v_cvt_pk_bf16_f32 v119, v114, v115
	global_store_dwordx4 v[192:193], v[116:119], off offset:256
	s_waitcnt vmcnt(12)
	v_lshlrev_b32_e32 v188, 16, v226
	v_and_b32_e32 v189, 0xffff0000, v226
	v_lshlrev_b32_e32 v190, 16, v227
	v_and_b32_e32 v191, 0xffff0000, v227
	v_lshlrev_b32_e32 v246, 16, v228
	v_and_b32_e32 v247, 0xffff0000, v228
	v_lshlrev_b32_e32 v248, 16, v229
	v_and_b32_e32 v249, 0xffff0000, v229
	global_load_dwordx4 v[226:229], v[148:149], off offset:256
	v_lshl_add_u64 v[150:151], v[172:173], 1, v[144:145]
	v_pk_fma_f32 v[108:109], v[108:109], v[92:93], v[188:189]
	v_pk_fma_f32 v[110:111], v[110:111], v[94:95], v[190:191]
	v_pk_fma_f32 v[104:105], v[104:105], v[84:85], v[246:247]
	v_pk_fma_f32 v[106:107], v[106:107], v[86:87], v[248:249]
	v_cvt_pk_bf16_f32 v108, v108, v109
	v_cvt_pk_bf16_f32 v109, v110, v111
	v_cvt_pk_bf16_f32 v110, v104, v105
	v_cvt_pk_bf16_f32 v111, v106, v107
	global_store_dwordx4 v[150:151], v[108:111], off
	s_waitcnt vmcnt(13)
	v_lshlrev_b32_e32 v188, 16, v230
	v_and_b32_e32 v189, 0xffff0000, v230
	v_lshlrev_b32_e32 v190, 16, v231
	v_and_b32_e32 v191, 0xffff0000, v231
	v_lshlrev_b32_e32 v246, 16, v232
	v_and_b32_e32 v247, 0xffff0000, v232
	v_lshlrev_b32_e32 v248, 16, v233
	v_and_b32_e32 v249, 0xffff0000, v233
	v_lshl_add_u64 v[148:149], v[182:183], 1, v[144:145]
	global_load_dwordx4 v[230:233], v[148:149], off
	v_pk_fma_f32 v[100:101], v[100:101], v[76:77], v[188:189]
	v_pk_fma_f32 v[102:103], v[102:103], v[78:79], v[190:191]
	v_pk_fma_f32 v[96:97], v[96:97], v[72:73], v[246:247]
	v_pk_fma_f32 v[98:99], v[98:99], v[74:75], v[248:249]
	v_cvt_pk_bf16_f32 v100, v100, v101
	v_cvt_pk_bf16_f32 v101, v102, v103
	v_cvt_pk_bf16_f32 v102, v96, v97
	v_cvt_pk_bf16_f32 v103, v98, v99
	global_store_dwordx4 v[150:151], v[100:103], off offset:256
	s_waitcnt vmcnt(14)
	v_lshlrev_b32_e32 v188, 16, v234
	v_and_b32_e32 v189, 0xffff0000, v234
	v_lshlrev_b32_e32 v190, 16, v235
	v_and_b32_e32 v191, 0xffff0000, v235
	v_lshlrev_b32_e32 v246, 16, v236
	v_and_b32_e32 v247, 0xffff0000, v236
	v_lshlrev_b32_e32 v248, 16, v237
	v_and_b32_e32 v249, 0xffff0000, v237
	global_load_dwordx4 v[234:237], v[148:149], off offset:256
	v_lshl_add_u64 v[192:193], v[174:175], 1, v[144:145]
	v_pk_fma_f32 v[88:89], v[88:89], v[92:93], v[188:189]
	v_pk_fma_f32 v[90:91], v[90:91], v[94:95], v[190:191]
	v_pk_fma_f32 v[80:81], v[80:81], v[84:85], v[246:247]
	v_pk_fma_f32 v[82:83], v[82:83], v[86:87], v[248:249]
	v_cvt_pk_bf16_f32 v88, v88, v89
	v_cvt_pk_bf16_f32 v89, v90, v91
	v_cvt_pk_bf16_f32 v90, v80, v81
	v_cvt_pk_bf16_f32 v91, v82, v83
	global_store_dwordx4 v[192:193], v[88:91], off
	s_waitcnt vmcnt(15)
	v_lshlrev_b32_e32 v188, 16, v238
	v_and_b32_e32 v189, 0xffff0000, v238
	v_lshlrev_b32_e32 v190, 16, v239
	v_and_b32_e32 v191, 0xffff0000, v239
	v_lshlrev_b32_e32 v246, 16, v240
	v_and_b32_e32 v247, 0xffff0000, v240
	v_lshlrev_b32_e32 v248, 16, v241
	v_and_b32_e32 v249, 0xffff0000, v241
	v_pk_fma_f32 v[68:69], v[68:69], v[76:77], v[188:189]
	v_pk_fma_f32 v[70:71], v[70:71], v[78:79], v[190:191]
	v_pk_fma_f32 v[64:65], v[64:65], v[72:73], v[246:247]
	v_pk_fma_f32 v[66:67], v[66:67], v[74:75], v[248:249]
	v_cvt_pk_bf16_f32 v68, v68, v69
	v_cvt_pk_bf16_f32 v69, v70, v71
	v_cvt_pk_bf16_f32 v70, v64, v65
	v_cvt_pk_bf16_f32 v71, v66, v67
	global_store_dwordx4 v[192:193], v[68:71], off offset:256
	s_waitcnt vmcnt(15)
	v_lshlrev_b32_e32 v188, 16, v242
	v_and_b32_e32 v189, 0xffff0000, v242
	v_lshlrev_b32_e32 v190, 16, v243
	v_and_b32_e32 v191, 0xffff0000, v243
	v_lshlrev_b32_e32 v246, 16, v244
	v_and_b32_e32 v247, 0xffff0000, v244
	v_lshlrev_b32_e32 v248, 16, v245
	v_and_b32_e32 v249, 0xffff0000, v245
	v_lshl_add_u64 v[150:151], v[176:177], 1, v[144:145]
	v_pk_fma_f32 v[60:61], v[60:61], v[92:93], v[188:189]
	v_pk_fma_f32 v[62:63], v[62:63], v[94:95], v[190:191]
	v_pk_fma_f32 v[56:57], v[56:57], v[84:85], v[246:247]
	v_pk_fma_f32 v[58:59], v[58:59], v[86:87], v[248:249]
	v_cvt_pk_bf16_f32 v60, v60, v61
	v_cvt_pk_bf16_f32 v61, v62, v63
	v_cvt_pk_bf16_f32 v62, v56, v57
	v_cvt_pk_bf16_f32 v63, v58, v59
	global_store_dwordx4 v[150:151], v[60:63], off
	s_waitcnt vmcnt(15)
	v_lshlrev_b32_e32 v188, 16, v210
	v_and_b32_e32 v189, 0xffff0000, v210
	v_lshlrev_b32_e32 v190, 16, v211
	v_and_b32_e32 v191, 0xffff0000, v211
	v_lshlrev_b32_e32 v246, 16, v212
	v_and_b32_e32 v247, 0xffff0000, v212
	v_lshlrev_b32_e32 v248, 16, v213
	v_and_b32_e32 v249, 0xffff0000, v213
	v_pk_fma_f32 v[52:53], v[52:53], v[76:77], v[188:189]
	v_pk_fma_f32 v[54:55], v[54:55], v[78:79], v[190:191]
	v_pk_fma_f32 v[48:49], v[48:49], v[72:73], v[246:247]
	v_pk_fma_f32 v[50:51], v[50:51], v[74:75], v[248:249]
	v_cvt_pk_bf16_f32 v52, v52, v53
	v_cvt_pk_bf16_f32 v53, v54, v55
	v_cvt_pk_bf16_f32 v54, v48, v49
	v_cvt_pk_bf16_f32 v55, v50, v51
	global_store_dwordx4 v[150:151], v[52:55], off offset:256
	s_waitcnt vmcnt(14)
	v_lshlrev_b32_e32 v188, 16, v214
	v_and_b32_e32 v189, 0xffff0000, v214
	v_lshlrev_b32_e32 v190, 16, v215
	v_and_b32_e32 v191, 0xffff0000, v215
	v_lshlrev_b32_e32 v246, 16, v216
	v_and_b32_e32 v247, 0xffff0000, v216
	v_lshlrev_b32_e32 v248, 16, v217
	v_and_b32_e32 v249, 0xffff0000, v217
	v_lshl_add_u64 v[192:193], v[178:179], 1, v[144:145]
	v_pk_fma_f32 v[44:45], v[44:45], v[92:93], v[188:189]
	v_pk_fma_f32 v[46:47], v[46:47], v[94:95], v[190:191]
	v_pk_fma_f32 v[40:41], v[40:41], v[84:85], v[246:247]
	v_pk_fma_f32 v[42:43], v[42:43], v[86:87], v[248:249]
	v_cvt_pk_bf16_f32 v44, v44, v45
	v_cvt_pk_bf16_f32 v45, v46, v47
	v_cvt_pk_bf16_f32 v46, v40, v41
	v_cvt_pk_bf16_f32 v47, v42, v43
	global_store_dwordx4 v[192:193], v[44:47], off
	s_waitcnt vmcnt(13)
	v_lshlrev_b32_e32 v188, 16, v218
	v_and_b32_e32 v189, 0xffff0000, v218
	v_lshlrev_b32_e32 v190, 16, v219
	v_and_b32_e32 v191, 0xffff0000, v219
	v_lshlrev_b32_e32 v246, 16, v220
	v_and_b32_e32 v247, 0xffff0000, v220
	v_lshlrev_b32_e32 v248, 16, v221
	v_and_b32_e32 v249, 0xffff0000, v221
	v_pk_fma_f32 v[36:37], v[36:37], v[76:77], v[188:189]
	v_pk_fma_f32 v[38:39], v[38:39], v[78:79], v[190:191]
	v_pk_fma_f32 v[32:33], v[32:33], v[72:73], v[246:247]
	v_pk_fma_f32 v[34:35], v[34:35], v[74:75], v[248:249]
	v_cvt_pk_bf16_f32 v36, v36, v37
	v_cvt_pk_bf16_f32 v37, v38, v39
	v_cvt_pk_bf16_f32 v38, v32, v33
	v_cvt_pk_bf16_f32 v39, v34, v35
	global_store_dwordx4 v[192:193], v[36:39], off offset:256
	s_waitcnt vmcnt(12)
	v_lshlrev_b32_e32 v188, 16, v222
	v_and_b32_e32 v189, 0xffff0000, v222
	v_lshlrev_b32_e32 v190, 16, v223
	v_and_b32_e32 v191, 0xffff0000, v223
	v_lshlrev_b32_e32 v246, 16, v224
	v_and_b32_e32 v247, 0xffff0000, v224
	v_lshlrev_b32_e32 v248, 16, v225
	v_and_b32_e32 v249, 0xffff0000, v225
	v_lshl_add_u64 v[150:151], v[180:181], 1, v[144:145]
	v_pk_fma_f32 v[28:29], v[28:29], v[92:93], v[188:189]
	v_pk_fma_f32 v[30:31], v[30:31], v[94:95], v[190:191]
	v_pk_fma_f32 v[24:25], v[24:25], v[84:85], v[246:247]
	v_pk_fma_f32 v[26:27], v[26:27], v[86:87], v[248:249]
	v_cvt_pk_bf16_f32 v28, v28, v29
	v_cvt_pk_bf16_f32 v29, v30, v31
	v_cvt_pk_bf16_f32 v30, v24, v25
	v_cvt_pk_bf16_f32 v31, v26, v27
	global_store_dwordx4 v[150:151], v[28:31], off
	s_waitcnt vmcnt(11)
	v_lshlrev_b32_e32 v188, 16, v226
	v_and_b32_e32 v189, 0xffff0000, v226
	v_lshlrev_b32_e32 v190, 16, v227
	v_and_b32_e32 v191, 0xffff0000, v227
	v_lshlrev_b32_e32 v246, 16, v228
	v_and_b32_e32 v247, 0xffff0000, v228
	v_lshlrev_b32_e32 v248, 16, v229
	v_and_b32_e32 v249, 0xffff0000, v229
	v_pk_fma_f32 v[20:21], v[20:21], v[76:77], v[188:189]
	v_pk_fma_f32 v[22:23], v[22:23], v[78:79], v[190:191]
	v_pk_fma_f32 v[16:17], v[16:17], v[72:73], v[246:247]
	v_pk_fma_f32 v[18:19], v[18:19], v[74:75], v[248:249]
	v_cvt_pk_bf16_f32 v20, v20, v21
	v_cvt_pk_bf16_f32 v21, v22, v23
	v_cvt_pk_bf16_f32 v22, v16, v17
	v_cvt_pk_bf16_f32 v23, v18, v19
	global_store_dwordx4 v[150:151], v[20:23], off offset:256
	s_waitcnt vmcnt(10)
	v_lshlrev_b32_e32 v188, 16, v230
	v_and_b32_e32 v189, 0xffff0000, v230
	v_lshlrev_b32_e32 v190, 16, v231
	v_and_b32_e32 v191, 0xffff0000, v231
	v_lshlrev_b32_e32 v246, 16, v232
	v_and_b32_e32 v247, 0xffff0000, v232
	v_lshlrev_b32_e32 v248, 16, v233
	v_and_b32_e32 v249, 0xffff0000, v233
	v_lshl_add_u64 v[192:193], v[182:183], 1, v[144:145]
	v_pk_fma_f32 v[12:13], v[12:13], v[92:93], v[188:189]
	v_pk_fma_f32 v[14:15], v[14:15], v[94:95], v[190:191]
	v_pk_fma_f32 v[8:9], v[8:9], v[84:85], v[246:247]
	v_pk_fma_f32 v[10:11], v[10:11], v[86:87], v[248:249]
	v_cvt_pk_bf16_f32 v12, v12, v13
	v_cvt_pk_bf16_f32 v13, v14, v15
	v_cvt_pk_bf16_f32 v14, v8, v9
	v_cvt_pk_bf16_f32 v15, v10, v11
	global_store_dwordx4 v[192:193], v[12:15], off
	s_waitcnt vmcnt(9)
	v_lshlrev_b32_e32 v188, 16, v234
	v_and_b32_e32 v189, 0xffff0000, v234
	v_lshlrev_b32_e32 v190, 16, v235
	v_and_b32_e32 v191, 0xffff0000, v235
	v_lshlrev_b32_e32 v246, 16, v236
	v_and_b32_e32 v247, 0xffff0000, v236
	v_lshlrev_b32_e32 v248, 16, v237
	v_and_b32_e32 v249, 0xffff0000, v237
	v_pk_fma_f32 v[4:5], v[4:5], v[76:77], v[188:189]
	v_pk_fma_f32 v[6:7], v[6:7], v[78:79], v[190:191]
	v_pk_fma_f32 v[0:1], v[0:1], v[72:73], v[246:247]
	v_pk_fma_f32 v[2:3], v[2:3], v[74:75], v[248:249]
	v_cvt_pk_bf16_f32 v4, v4, v5
	v_cvt_pk_bf16_f32 v5, v6, v7
	v_cvt_pk_bf16_f32 v6, v0, v1
	v_cvt_pk_bf16_f32 v7, v2, v3
	global_store_dwordx4 v[192:193], v[4:7], off offset:256
	s_branch .Lwo_epi_done

.LBB0_772:
	s_ashr_i32 s35, s34, 31
	v_cmp_lt_i64_e32 vcc, s[42:43], v[156:157]
	s_lshl_b64 s[42:43], s[34:35], 20
	s_add_u32 s42, s15, s42
	s_addc_u32 s43, s30, s43
	s_and_b64 s[44:45], vcc, exec
	s_cselect_b32 s35, s43, s21
	s_cselect_b32 s56, s42, s20
	s_ashr_i32 s25, s24, 31
	s_lshl_b64 s[44:45], s[24:25], 20
	s_add_u32 s44, s48, s44
	s_addc_u32 s45, s49, s45
	s_and_b64 s[46:47], vcc, exec
	s_cselect_b32 s25, s45, s23
	s_cselect_b32 s57, s44, s22
	s_add_u32 s20, s20, 0x80080
	s_addc_u32 s21, s21, 0
	s_add_u32 s58, s22, 0x100
	v_mov_b32_e32 v0, 0
	s_addc_u32 s59, s23, 0
	s_mov_b32 s60, -2
	v_mov_b32_e32 v1, v0
	v_mov_b32_e32 v2, v0
	v_mov_b32_e32 v3, v0
	v_mov_b32_e32 v4, v0
	v_mov_b32_e32 v5, v0
	v_mov_b32_e32 v6, v0
	v_mov_b32_e32 v7, v0
	v_mov_b32_e32 v16, v0
	v_mov_b32_e32 v17, v0
	v_mov_b32_e32 v18, v0
	v_mov_b32_e32 v19, v0
	v_mov_b32_e32 v20, v0
	v_mov_b32_e32 v21, v0
	v_mov_b32_e32 v22, v0
	v_mov_b32_e32 v23, v0
	v_mov_b32_e32 v32, v0
	v_mov_b32_e32 v33, v0
	v_mov_b32_e32 v34, v0
	v_mov_b32_e32 v35, v0
	v_mov_b32_e32 v36, v0
	v_mov_b32_e32 v37, v0
	v_mov_b32_e32 v38, v0
	v_mov_b32_e32 v39, v0
	v_mov_b32_e32 v48, v0
	v_mov_b32_e32 v49, v0
	v_mov_b32_e32 v50, v0
	v_mov_b32_e32 v51, v0
	v_mov_b32_e32 v52, v0
	v_mov_b32_e32 v53, v0
	v_mov_b32_e32 v54, v0
	v_mov_b32_e32 v55, v0
	v_mov_b32_e32 v8, v0
	v_mov_b32_e32 v9, v0
	v_mov_b32_e32 v10, v0
	v_mov_b32_e32 v11, v0
	v_mov_b32_e32 v12, v0
	v_mov_b32_e32 v13, v0
	v_mov_b32_e32 v14, v0
	v_mov_b32_e32 v15, v0
	v_mov_b32_e32 v24, v0
	v_mov_b32_e32 v25, v0
	v_mov_b32_e32 v26, v0
	v_mov_b32_e32 v27, v0
	v_mov_b32_e32 v28, v0
	v_mov_b32_e32 v29, v0
	v_mov_b32_e32 v30, v0
	v_mov_b32_e32 v31, v0
	v_mov_b32_e32 v40, v0
	v_mov_b32_e32 v41, v0
	v_mov_b32_e32 v42, v0
	v_mov_b32_e32 v43, v0
	v_mov_b32_e32 v44, v0
	v_mov_b32_e32 v45, v0
	v_mov_b32_e32 v46, v0
	v_mov_b32_e32 v47, v0
	v_mov_b32_e32 v56, v0
	v_mov_b32_e32 v57, v0
	v_mov_b32_e32 v58, v0
	v_mov_b32_e32 v59, v0
	v_mov_b32_e32 v60, v0
	v_mov_b32_e32 v61, v0
	v_mov_b32_e32 v62, v0
	v_mov_b32_e32 v63, v0
	v_mov_b32_e32 v64, v0
	v_mov_b32_e32 v65, v0
	v_mov_b32_e32 v66, v0
	v_mov_b32_e32 v67, v0
	v_mov_b32_e32 v68, v0
	v_mov_b32_e32 v69, v0
	v_mov_b32_e32 v70, v0
	v_mov_b32_e32 v71, v0
	v_mov_b32_e32 v80, v0
	v_mov_b32_e32 v81, v0
	v_mov_b32_e32 v82, v0
	v_mov_b32_e32 v83, v0
	v_mov_b32_e32 v84, v0
	v_mov_b32_e32 v85, v0
	v_mov_b32_e32 v86, v0
	v_mov_b32_e32 v87, v0
	v_mov_b32_e32 v96, v0
	v_mov_b32_e32 v97, v0
	v_mov_b32_e32 v98, v0
	v_mov_b32_e32 v99, v0
	v_mov_b32_e32 v100, v0
	v_mov_b32_e32 v101, v0
	v_mov_b32_e32 v102, v0
	v_mov_b32_e32 v103, v0
	v_mov_b32_e32 v112, v0
	v_mov_b32_e32 v113, v0
	v_mov_b32_e32 v114, v0
	v_mov_b32_e32 v115, v0
	v_mov_b32_e32 v116, v0
	v_mov_b32_e32 v117, v0
	v_mov_b32_e32 v118, v0
	v_mov_b32_e32 v119, v0
	v_mov_b32_e32 v72, v0
	v_mov_b32_e32 v73, v0
	v_mov_b32_e32 v74, v0
	v_mov_b32_e32 v75, v0
	v_mov_b32_e32 v76, v0
	v_mov_b32_e32 v77, v0
	v_mov_b32_e32 v78, v0
	v_mov_b32_e32 v79, v0
	v_mov_b32_e32 v88, v0
	v_mov_b32_e32 v89, v0
	v_mov_b32_e32 v90, v0
	v_mov_b32_e32 v91, v0
	v_mov_b32_e32 v92, v0
	v_mov_b32_e32 v93, v0
	v_mov_b32_e32 v94, v0
	v_mov_b32_e32 v95, v0
	v_mov_b32_e32 v104, v0
	v_mov_b32_e32 v105, v0
	v_mov_b32_e32 v106, v0
	v_mov_b32_e32 v107, v0
	v_mov_b32_e32 v108, v0
	v_mov_b32_e32 v109, v0
	v_mov_b32_e32 v110, v0
	v_mov_b32_e32 v111, v0
	v_mov_b32_e32 v120, v0
	v_mov_b32_e32 v121, v0
	v_mov_b32_e32 v122, v0
	v_mov_b32_e32 v123, v0
	v_mov_b32_e32 v124, v0
	v_mov_b32_e32 v125, v0
	v_mov_b32_e32 v126, v0
	v_mov_b32_e32 v127, v0
	v_add_u32_e32 v230, 0x10000, v141
	v_add_u32_e32 v231, 0x14000, v141
	v_add_u32_e32 v232, 0x18000, v141
	v_add_u32_e32 v233, 0x1c000, v141
.LBB0_773:
	s_add_u32 s22, s20, 0xfff80080
	s_addc_u32 s23, s21, -1
	s_add_i32 s61, 0, 0x10000
	ds_read_b128 v[144:147], v230
	ds_read_b128 v[148:151], v230 offset:1024
	ds_read_b128 v[162:165], v230 offset:2048
	ds_read_b128 v[166:169], v230 offset:3072
	s_cmp_eq_u32 s60, 28
	s_cselect_b32 s47, s35, s23
	s_cselect_b32 s46, s56, s22
	s_cselect_b32 s23, s25, s59
	s_cselect_b32 s22, s57, s58
	s_add_i32 m0, s5, 0xc000
	ds_read_b128 v[170:173], v143
	ds_read_b128 v[174:177], v143 offset:1024
	ds_read_b128 v[178:181], v143 offset:2048
	ds_read_b128 v[182:185], v143 offset:3072
	ds_read_b128 v[186:189], v143 offset:4096
	ds_read_b128 v[190:193], v143 offset:5120
	ds_read_b128 v[206:209], v143 offset:6144
	ds_read_b128 v[210:213], v143 offset:7168
	global_load_lds_dwordx4 v134, s[20:21]
	s_add_i32 m0, s5, 0xe000
	s_nop 0
	global_load_lds_dwordx4 v136, s[20:21]
	s_waitcnt lgkmcnt(8)
	s_barrier
	s_waitcnt lgkmcnt(0)
	s_setprio 1
	s_waitcnt lgkmcnt(0)
	v_mfma_f32_16x16x32_bf16 v[124:127], v[144:147], v[170:173], v[124:127]
	v_mfma_f32_16x16x32_bf16 v[120:123], v[162:165], v[170:173], v[120:123]
	v_mfma_f32_16x16x32_bf16 v[108:111], v[144:147], v[178:181], v[108:111]
	v_mfma_f32_16x16x32_bf16 v[104:107], v[162:165], v[178:181], v[104:107]
	v_mfma_f32_16x16x32_bf16 v[92:95], v[144:147], v[186:189], v[92:95]
	v_mfma_f32_16x16x32_bf16 v[88:91], v[162:165], v[186:189], v[88:91]
	v_mfma_f32_16x16x32_bf16 v[76:79], v[144:147], v[206:209], v[76:79]
	v_mfma_f32_16x16x32_bf16 v[72:75], v[162:165], v[206:209], v[72:75]
	v_mfma_f32_16x16x32_bf16 v[124:127], v[148:151], v[174:177], v[124:127]
	v_mfma_f32_16x16x32_bf16 v[120:123], v[166:169], v[174:177], v[120:123]
	v_mfma_f32_16x16x32_bf16 v[108:111], v[148:151], v[182:185], v[108:111]
	v_mfma_f32_16x16x32_bf16 v[104:107], v[166:169], v[182:185], v[104:107]
	v_mfma_f32_16x16x32_bf16 v[92:95], v[148:151], v[190:193], v[92:95]
	v_mfma_f32_16x16x32_bf16 v[88:91], v[166:169], v[190:193], v[88:91]
	v_mfma_f32_16x16x32_bf16 v[76:79], v[148:151], v[210:213], v[76:79]
	v_mfma_f32_16x16x32_bf16 v[72:75], v[166:169], v[210:213], v[72:75]
	s_setprio 0
	s_barrier
	s_add_i32 s68, 0, 0x14000
	s_add_i32 s61, s61, s4
	ds_read_b128 v[214:217], v231
	ds_read_b128 v[218:221], v231 offset:1024
	ds_read_b128 v[222:225], v231 offset:2048
	ds_read_b128 v[226:229], v231 offset:3072
	s_mov_b32 m0, s61
	s_nop 0
	global_load_lds_dwordx4 v152, s[22:23]
	s_add_i32 m0, s61, 0x2000
	s_nop 0
	global_load_lds_dwordx4 v132, s[22:23]
	s_barrier
	s_waitcnt lgkmcnt(0)
	s_setprio 1
	s_waitcnt lgkmcnt(0)
	v_mfma_f32_16x16x32_bf16 v[116:119], v[214:217], v[170:173], v[116:119]
	v_mfma_f32_16x16x32_bf16 v[112:115], v[222:225], v[170:173], v[112:115]
	v_mfma_f32_16x16x32_bf16 v[100:103], v[214:217], v[178:181], v[100:103]
	v_mfma_f32_16x16x32_bf16 v[96:99], v[222:225], v[178:181], v[96:99]
	v_mfma_f32_16x16x32_bf16 v[84:87], v[214:217], v[186:189], v[84:87]
	v_mfma_f32_16x16x32_bf16 v[80:83], v[222:225], v[186:189], v[80:83]
	v_mfma_f32_16x16x32_bf16 v[68:71], v[214:217], v[206:209], v[68:71]
	v_mfma_f32_16x16x32_bf16 v[64:67], v[222:225], v[206:209], v[64:67]
	v_mfma_f32_16x16x32_bf16 v[116:119], v[218:221], v[174:177], v[116:119]
	v_mfma_f32_16x16x32_bf16 v[112:115], v[226:229], v[174:177], v[112:115]
	v_mfma_f32_16x16x32_bf16 v[100:103], v[218:221], v[182:185], v[100:103]
	v_mfma_f32_16x16x32_bf16 v[96:99], v[226:229], v[182:185], v[96:99]
	v_mfma_f32_16x16x32_bf16 v[84:87], v[218:221], v[190:193], v[84:87]
	v_mfma_f32_16x16x32_bf16 v[80:83], v[226:229], v[190:193], v[80:83]
	v_mfma_f32_16x16x32_bf16 v[68:71], v[218:221], v[210:213], v[68:71]
	v_mfma_f32_16x16x32_bf16 v[64:67], v[226:229], v[210:213], v[64:67]
	s_setprio 0
	s_mov_b32 m0, s5
	s_add_u32 s98, s46, 0x80
	s_addc_u32 s99, s47, 0
	s_barrier
	ds_read_b128 v[170:173], v143 offset:16384
	ds_read_b128 v[174:177], v143 offset:17408
	ds_read_b128 v[178:181], v143 offset:18432
	ds_read_b128 v[182:185], v143 offset:19456
	ds_read_b128 v[186:189], v143 offset:20480
	ds_read_b128 v[190:193], v143 offset:21504
	ds_read_b128 v[206:209], v143 offset:22528
	ds_read_b128 v[210:213], v143 offset:23552
	global_load_lds_dwordx4 v128, s[46:47]
	s_mov_b32 m0, s50
	s_nop 0
	global_load_lds_dwordx4 v130, s[46:47]
	s_barrier
	s_waitcnt lgkmcnt(0)
	s_setprio 1
	s_waitcnt lgkmcnt(0)
	v_mfma_f32_16x16x32_bf16 v[60:63], v[144:147], v[170:173], v[60:63]
	v_mfma_f32_16x16x32_bf16 v[56:59], v[162:165], v[170:173], v[56:59]
	v_mfma_f32_16x16x32_bf16 v[44:47], v[144:147], v[178:181], v[44:47]
	v_mfma_f32_16x16x32_bf16 v[40:43], v[162:165], v[178:181], v[40:43]
	v_mfma_f32_16x16x32_bf16 v[28:31], v[144:147], v[186:189], v[28:31]
	v_mfma_f32_16x16x32_bf16 v[24:27], v[162:165], v[186:189], v[24:27]
	v_mfma_f32_16x16x32_bf16 v[12:15], v[144:147], v[206:209], v[12:15]
	v_mfma_f32_16x16x32_bf16 v[8:11], v[162:165], v[206:209], v[8:11]
	v_mfma_f32_16x16x32_bf16 v[60:63], v[148:151], v[174:177], v[60:63]
	v_mfma_f32_16x16x32_bf16 v[56:59], v[166:169], v[174:177], v[56:59]
	v_mfma_f32_16x16x32_bf16 v[44:47], v[148:151], v[182:185], v[44:47]
	v_mfma_f32_16x16x32_bf16 v[40:43], v[166:169], v[182:185], v[40:43]
	v_mfma_f32_16x16x32_bf16 v[28:31], v[148:151], v[190:193], v[28:31]
	v_mfma_f32_16x16x32_bf16 v[24:27], v[166:169], v[190:193], v[24:27]
	v_mfma_f32_16x16x32_bf16 v[12:15], v[148:151], v[210:213], v[12:15]
	v_mfma_f32_16x16x32_bf16 v[8:11], v[166:169], v[210:213], v[8:11]
	s_setprio 0
	s_barrier
	s_add_u32 s62, s22, 0x80000
	s_addc_u32 s63, s23, 0
	s_add_i32 s61, s68, s4
	s_mov_b32 m0, s61
	s_nop 0
	global_load_lds_dwordx4 v152, s[62:63]
	s_add_i32 m0, s61, 0x2000
	s_nop 0
	global_load_lds_dwordx4 v132, s[62:63]
	s_waitcnt vmcnt(6)
	s_barrier
	s_setprio 1
	v_mfma_f32_16x16x32_bf16 v[52:55], v[214:217], v[170:173], v[52:55]
	v_mfma_f32_16x16x32_bf16 v[48:51], v[222:225], v[170:173], v[48:51]
	v_mfma_f32_16x16x32_bf16 v[36:39], v[214:217], v[178:181], v[36:39]
	v_mfma_f32_16x16x32_bf16 v[32:35], v[222:225], v[178:181], v[32:35]
	v_mfma_f32_16x16x32_bf16 v[20:23], v[214:217], v[186:189], v[20:23]
	v_mfma_f32_16x16x32_bf16 v[16:19], v[222:225], v[186:189], v[16:19]
	v_mfma_f32_16x16x32_bf16 v[4:7], v[214:217], v[206:209], v[4:7]
	v_mfma_f32_16x16x32_bf16 v[0:3], v[222:225], v[206:209], v[0:3]
	v_mfma_f32_16x16x32_bf16 v[52:55], v[218:221], v[174:177], v[52:55]
	v_mfma_f32_16x16x32_bf16 v[48:51], v[226:229], v[174:177], v[48:51]
	v_mfma_f32_16x16x32_bf16 v[36:39], v[218:221], v[182:185], v[36:39]
	v_mfma_f32_16x16x32_bf16 v[32:35], v[226:229], v[182:185], v[32:35]
	v_mfma_f32_16x16x32_bf16 v[20:23], v[218:221], v[190:193], v[20:23]
	v_mfma_f32_16x16x32_bf16 v[16:19], v[226:229], v[190:193], v[16:19]
	v_mfma_f32_16x16x32_bf16 v[4:7], v[218:221], v[210:213], v[4:7]
	v_mfma_f32_16x16x32_bf16 v[0:3], v[226:229], v[210:213], v[0:3]
	s_setprio 0
	s_add_i32 s61, 0, 0x18000
	s_barrier
	ds_read_b128 v[144:147], v232
	ds_read_b128 v[148:151], v232 offset:1024
	ds_read_b128 v[162:165], v232 offset:2048
	ds_read_b128 v[166:169], v232 offset:3072
	s_add_u32 s46, s46, 0x80000
	s_addc_u32 s47, s47, 0
	s_mov_b32 m0, s51
	ds_read_b128 v[170:173], v143 offset:32768
	ds_read_b128 v[174:177], v143 offset:33792
	ds_read_b128 v[178:181], v143 offset:34816
	ds_read_b128 v[182:185], v143 offset:35840
	ds_read_b128 v[186:189], v143 offset:36864
	ds_read_b128 v[190:193], v143 offset:37888
	ds_read_b128 v[206:209], v143 offset:38912
	ds_read_b128 v[210:213], v143 offset:39936
	global_load_lds_dwordx4 v128, s[46:47]
	s_mov_b32 m0, s52
	s_nop 0
	global_load_lds_dwordx4 v130, s[46:47]
	s_waitcnt lgkmcnt(8)
	s_barrier
	s_waitcnt lgkmcnt(0)
	s_setprio 1
	s_waitcnt lgkmcnt(0)
	v_mfma_f32_16x16x32_bf16 v[124:127], v[144:147], v[170:173], v[124:127]
	v_mfma_f32_16x16x32_bf16 v[120:123], v[162:165], v[170:173], v[120:123]
	v_mfma_f32_16x16x32_bf16 v[108:111], v[144:147], v[178:181], v[108:111]
	v_mfma_f32_16x16x32_bf16 v[104:107], v[162:165], v[178:181], v[104:107]
	v_mfma_f32_16x16x32_bf16 v[92:95], v[144:147], v[186:189], v[92:95]
	v_mfma_f32_16x16x32_bf16 v[88:91], v[162:165], v[186:189], v[88:91]
	v_mfma_f32_16x16x32_bf16 v[76:79], v[144:147], v[206:209], v[76:79]
	v_mfma_f32_16x16x32_bf16 v[72:75], v[162:165], v[206:209], v[72:75]
	v_mfma_f32_16x16x32_bf16 v[124:127], v[148:151], v[174:177], v[124:127]
	v_mfma_f32_16x16x32_bf16 v[120:123], v[166:169], v[174:177], v[120:123]
	v_mfma_f32_16x16x32_bf16 v[108:111], v[148:151], v[182:185], v[108:111]
	v_mfma_f32_16x16x32_bf16 v[104:107], v[166:169], v[182:185], v[104:107]
	v_mfma_f32_16x16x32_bf16 v[92:95], v[148:151], v[190:193], v[92:95]
	v_mfma_f32_16x16x32_bf16 v[88:91], v[166:169], v[190:193], v[88:91]
	v_mfma_f32_16x16x32_bf16 v[76:79], v[148:151], v[210:213], v[76:79]
	v_mfma_f32_16x16x32_bf16 v[72:75], v[166:169], v[210:213], v[72:75]
	s_setprio 0
	s_barrier
	s_add_i32 s46, 0, 0x1c000
	s_add_i32 s47, s61, s4
	s_add_u32 s100, s22, 0x80
	s_addc_u32 s101, s23, 0
	s_mov_b32 m0, s47
	ds_read_b128 v[214:217], v233
	ds_read_b128 v[218:221], v233 offset:1024
	ds_read_b128 v[222:225], v233 offset:2048
	ds_read_b128 v[226:229], v233 offset:3072
	global_load_lds_dwordx4 v152, s[100:101]
	s_add_i32 m0, s47, 0x2000
	s_nop 0
	global_load_lds_dwordx4 v132, s[100:101]
	s_barrier
	s_waitcnt lgkmcnt(0)
	s_setprio 1
	s_waitcnt lgkmcnt(0)
	v_mfma_f32_16x16x32_bf16 v[116:119], v[214:217], v[170:173], v[116:119]
	v_mfma_f32_16x16x32_bf16 v[112:115], v[222:225], v[170:173], v[112:115]
	v_mfma_f32_16x16x32_bf16 v[100:103], v[214:217], v[178:181], v[100:103]
	v_mfma_f32_16x16x32_bf16 v[96:99], v[222:225], v[178:181], v[96:99]
	v_mfma_f32_16x16x32_bf16 v[84:87], v[214:217], v[186:189], v[84:87]
	v_mfma_f32_16x16x32_bf16 v[80:83], v[222:225], v[186:189], v[80:83]
	v_mfma_f32_16x16x32_bf16 v[68:71], v[214:217], v[206:209], v[68:71]
	v_mfma_f32_16x16x32_bf16 v[64:67], v[222:225], v[206:209], v[64:67]
	v_mfma_f32_16x16x32_bf16 v[116:119], v[218:221], v[174:177], v[116:119]
	v_mfma_f32_16x16x32_bf16 v[112:115], v[226:229], v[174:177], v[112:115]
	v_mfma_f32_16x16x32_bf16 v[100:103], v[218:221], v[182:185], v[100:103]
	v_mfma_f32_16x16x32_bf16 v[96:99], v[226:229], v[182:185], v[96:99]
	v_mfma_f32_16x16x32_bf16 v[84:87], v[218:221], v[190:193], v[84:87]
	v_mfma_f32_16x16x32_bf16 v[80:83], v[226:229], v[190:193], v[80:83]
	v_mfma_f32_16x16x32_bf16 v[68:71], v[218:221], v[210:213], v[68:71]
	v_mfma_f32_16x16x32_bf16 v[64:67], v[226:229], v[210:213], v[64:67]
	s_setprio 0
	s_mov_b32 m0, s53
	s_barrier
	ds_read_b128 v[170:173], v143 offset:49152
	ds_read_b128 v[174:177], v143 offset:50176
	ds_read_b128 v[178:181], v143 offset:51200
	ds_read_b128 v[182:185], v143 offset:52224
	ds_read_b128 v[186:189], v143 offset:53248
	ds_read_b128 v[190:193], v143 offset:54272
	ds_read_b128 v[206:209], v143 offset:55296
	ds_read_b128 v[210:213], v143 offset:56320
	global_load_lds_dwordx4 v128, s[98:99]
	s_mov_b32 m0, s54
	s_nop 0
	global_load_lds_dwordx4 v130, s[98:99]
	s_barrier
	s_waitcnt lgkmcnt(0)
	s_setprio 1
	s_waitcnt lgkmcnt(0)
	v_mfma_f32_16x16x32_bf16 v[60:63], v[144:147], v[170:173], v[60:63]
	v_mfma_f32_16x16x32_bf16 v[56:59], v[162:165], v[170:173], v[56:59]
	v_mfma_f32_16x16x32_bf16 v[44:47], v[144:147], v[178:181], v[44:47]
	v_mfma_f32_16x16x32_bf16 v[40:43], v[162:165], v[178:181], v[40:43]
	v_mfma_f32_16x16x32_bf16 v[28:31], v[144:147], v[186:189], v[28:31]
	v_mfma_f32_16x16x32_bf16 v[24:27], v[162:165], v[186:189], v[24:27]
	v_mfma_f32_16x16x32_bf16 v[12:15], v[144:147], v[206:209], v[12:15]
	v_mfma_f32_16x16x32_bf16 v[8:11], v[162:165], v[206:209], v[8:11]
	v_mfma_f32_16x16x32_bf16 v[60:63], v[148:151], v[174:177], v[60:63]
	v_mfma_f32_16x16x32_bf16 v[56:59], v[166:169], v[174:177], v[56:59]
	v_mfma_f32_16x16x32_bf16 v[44:47], v[148:151], v[182:185], v[44:47]
	v_mfma_f32_16x16x32_bf16 v[40:43], v[166:169], v[182:185], v[40:43]
	v_mfma_f32_16x16x32_bf16 v[28:31], v[148:151], v[190:193], v[28:31]
	v_mfma_f32_16x16x32_bf16 v[24:27], v[166:169], v[190:193], v[24:27]
	v_mfma_f32_16x16x32_bf16 v[12:15], v[148:151], v[210:213], v[12:15]
	v_mfma_f32_16x16x32_bf16 v[8:11], v[166:169], v[210:213], v[8:11]
	s_setprio 0
	s_barrier
	s_add_u32 s22, s22, 0x80080
	s_addc_u32 s23, s23, 0
	s_add_i32 s46, s46, s4
	s_mov_b32 m0, s46
	s_nop 0
	global_load_lds_dwordx4 v152, s[22:23]
	s_add_i32 m0, s46, 0x2000
	s_nop 0
	global_load_lds_dwordx4 v132, s[22:23]
	s_waitcnt vmcnt(6)
	s_barrier
	s_setprio 1
	v_mfma_f32_16x16x32_bf16 v[52:55], v[214:217], v[170:173], v[52:55]
	v_mfma_f32_16x16x32_bf16 v[48:51], v[222:225], v[170:173], v[48:51]
	v_mfma_f32_16x16x32_bf16 v[36:39], v[214:217], v[178:181], v[36:39]
	v_mfma_f32_16x16x32_bf16 v[32:35], v[222:225], v[178:181], v[32:35]
	v_mfma_f32_16x16x32_bf16 v[20:23], v[214:217], v[186:189], v[20:23]
	v_mfma_f32_16x16x32_bf16 v[16:19], v[222:225], v[186:189], v[16:19]
	v_mfma_f32_16x16x32_bf16 v[4:7], v[214:217], v[206:209], v[4:7]
	v_mfma_f32_16x16x32_bf16 v[0:3], v[222:225], v[206:209], v[0:3]
	v_mfma_f32_16x16x32_bf16 v[52:55], v[218:221], v[174:177], v[52:55]
	v_mfma_f32_16x16x32_bf16 v[48:51], v[226:229], v[174:177], v[48:51]
	v_mfma_f32_16x16x32_bf16 v[36:39], v[218:221], v[182:185], v[36:39]
	v_mfma_f32_16x16x32_bf16 v[32:35], v[226:229], v[182:185], v[32:35]
	v_mfma_f32_16x16x32_bf16 v[20:23], v[218:221], v[190:193], v[20:23]
	v_mfma_f32_16x16x32_bf16 v[16:19], v[226:229], v[190:193], v[16:19]
	v_mfma_f32_16x16x32_bf16 v[4:7], v[218:221], v[210:213], v[4:7]
	v_mfma_f32_16x16x32_bf16 v[0:3], v[226:229], v[210:213], v[0:3]
	s_setprio 0
	s_add_i32 s60, s60, 2
	s_add_u32 s20, s20, 0x100
	s_addc_u32 s21, s21, 0
	s_add_u32 s58, s58, 0x100
	s_addc_u32 s59, s59, 0
	s_cmp_gt_u32 s60, 29
	s_barrier
	s_cbranch_scc0 .LBB0_773
	v_lshl_add_u32 v144, s7, 8, v140
	v_max_f32_e32 v120, v120, v120
	v_ashrrev_i32_e32 v145, 31, v144
	v_max_f32_e32 v120, 0, v120
	v_max_f32_e32 v121, v121, v121
	v_max_f32_e32 v122, v122, v122
	v_lshl_or_b32 v138, s6, 8, v142
	v_lshlrev_b64 v[146:147], 14, v[144:145]
	v_mul_f32_e32 v145, v120, v120
	v_max_f32_e32 v120, v125, v125
	v_max_f32_e32 v121, 0, v121
	v_max_f32_e32 v122, 0, v122
	v_ashrrev_i32_e32 v139, 31, v138
	v_max_f32_e32 v124, v124, v124
	v_max_f32_e32 v120, 0, v120
	v_mul_f32_e32 v125, v121, v121
	v_max_f32_e32 v121, v126, v126
	v_mul_f32_e32 v126, v122, v122
	v_max_f32_e32 v122, v127, v127
	v_max_f32_e32 v123, v123, v123
	v_lshl_add_u64 v[146:147], s[16:17], 0, v[146:147]
	v_lshlrev_b64 v[148:149], 1, v[138:139]
	v_max_f32_e32 v124, 0, v124
	v_mul_f32_e32 v120, v120, v120
	v_max_f32_e32 v121, 0, v121
	v_max_f32_e32 v122, 0, v122
	v_max_f32_e32 v123, 0, v123
	v_max_f32_e32 v112, v112, v112
	v_lshl_add_u64 v[138:139], v[146:147], 0, v[148:149]
	v_mul_f32_e32 v124, v124, v124
	v_mul_f32_e32 v121, v121, v121
	v_mul_f32_e32 v122, v122, v122
	v_mul_f32_e32 v123, v123, v123
	v_cvt_pk_bf16_f32 v120, v124, v120
	v_max_f32_e32 v112, 0, v112
	v_max_f32_e32 v113, v113, v113
	v_max_f32_e32 v114, v114, v114
	v_cvt_pk_bf16_f32 v121, v121, v122
	v_cvt_pk_bf16_f32 v122, v145, v125
	v_cvt_pk_bf16_f32 v123, v126, v123
	global_store_dwordx4 v[138:139], v[120:123], off
	v_max_f32_e32 v113, 0, v113
	v_max_f32_e32 v114, 0, v114
	v_mul_f32_e32 v120, v112, v112
	v_max_f32_e32 v112, v117, v117
	v_max_f32_e32 v116, v116, v116
	v_max_f32_e32 v112, 0, v112
	v_mul_f32_e32 v117, v113, v113
	v_max_f32_e32 v113, v118, v118
	v_mul_f32_e32 v118, v114, v114
	v_max_f32_e32 v114, v119, v119
	v_max_f32_e32 v115, v115, v115
	v_max_f32_e32 v116, 0, v116
	v_mul_f32_e32 v112, v112, v112
	v_max_f32_e32 v113, 0, v113
	v_max_f32_e32 v114, 0, v114
	v_max_f32_e32 v115, 0, v115
	v_mul_f32_e32 v116, v116, v116
	v_mul_f32_e32 v113, v113, v113
	v_mul_f32_e32 v114, v114, v114
	v_mul_f32_e32 v115, v115, v115
	v_cvt_pk_bf16_f32 v112, v116, v112
	v_max_f32_e32 v104, v104, v104
	v_cvt_pk_bf16_f32 v113, v113, v114
	v_cvt_pk_bf16_f32 v114, v120, v117
	v_cvt_pk_bf16_f32 v115, v118, v115
	global_store_dwordx4 v[138:139], v[112:115], off offset:256
	v_max_f32_e32 v104, 0, v104
	v_max_f32_e32 v105, v105, v105
	v_or_b32_e32 v112, 16, v144
	v_max_f32_e32 v106, v106, v106
	v_ashrrev_i32_e32 v113, 31, v112
	v_mul_f32_e32 v114, v104, v104
	v_max_f32_e32 v104, v109, v109
	v_max_f32_e32 v105, 0, v105
	v_max_f32_e32 v106, 0, v106
	v_lshlrev_b64 v[112:113], 14, v[112:113]
	v_max_f32_e32 v108, v108, v108
	v_max_f32_e32 v104, 0, v104
	v_mul_f32_e32 v109, v105, v105
	v_max_f32_e32 v105, v110, v110
	v_mul_f32_e32 v110, v106, v106
	v_max_f32_e32 v106, v111, v111
	v_max_f32_e32 v107, v107, v107
	v_lshl_add_u64 v[112:113], s[16:17], 0, v[112:113]
	v_max_f32_e32 v108, 0, v108
	v_mul_f32_e32 v104, v104, v104
	v_max_f32_e32 v105, 0, v105
	v_max_f32_e32 v106, 0, v106
	v_max_f32_e32 v107, 0, v107
	v_max_f32_e32 v96, v96, v96
	v_lshl_add_u64 v[112:113], v[112:113], 0, v[148:149]
	v_mul_f32_e32 v108, v108, v108
	v_mul_f32_e32 v105, v105, v105
	v_mul_f32_e32 v106, v106, v106
	v_mul_f32_e32 v107, v107, v107
	v_cvt_pk_bf16_f32 v104, v108, v104
	v_max_f32_e32 v96, 0, v96
	v_max_f32_e32 v97, v97, v97
	v_max_f32_e32 v98, v98, v98
	v_cvt_pk_bf16_f32 v105, v105, v106
	v_cvt_pk_bf16_f32 v106, v114, v109
	v_cvt_pk_bf16_f32 v107, v110, v107
	global_store_dwordx4 v[112:113], v[104:107], off
	v_max_f32_e32 v97, 0, v97
	v_max_f32_e32 v98, 0, v98
	v_mul_f32_e32 v104, v96, v96
	v_max_f32_e32 v96, v101, v101
	v_max_f32_e32 v100, v100, v100
	v_max_f32_e32 v96, 0, v96
	v_mul_f32_e32 v101, v97, v97
	v_max_f32_e32 v97, v102, v102
	v_mul_f32_e32 v102, v98, v98
	v_max_f32_e32 v98, v103, v103
	v_max_f32_e32 v99, v99, v99
	v_max_f32_e32 v100, 0, v100
	v_mul_f32_e32 v96, v96, v96
	v_max_f32_e32 v97, 0, v97
	v_max_f32_e32 v98, 0, v98
	v_max_f32_e32 v99, 0, v99
	v_mul_f32_e32 v100, v100, v100
	v_mul_f32_e32 v97, v97, v97
	v_mul_f32_e32 v98, v98, v98
	v_mul_f32_e32 v99, v99, v99
	v_cvt_pk_bf16_f32 v96, v100, v96
	v_max_f32_e32 v88, v88, v88
	v_cvt_pk_bf16_f32 v97, v97, v98
	v_cvt_pk_bf16_f32 v98, v104, v101
	v_cvt_pk_bf16_f32 v99, v102, v99
	global_store_dwordx4 v[112:113], v[96:99], off offset:256
	v_max_f32_e32 v88, 0, v88
	v_max_f32_e32 v89, v89, v89
	v_or_b32_e32 v96, 32, v144
	v_max_f32_e32 v90, v90, v90
	v_ashrrev_i32_e32 v97, 31, v96
	v_mul_f32_e32 v98, v88, v88
	v_max_f32_e32 v88, v93, v93
	v_max_f32_e32 v89, 0, v89
	v_max_f32_e32 v90, 0, v90
	v_lshlrev_b64 v[96:97], 14, v[96:97]
	v_max_f32_e32 v92, v92, v92
	v_max_f32_e32 v88, 0, v88
	v_mul_f32_e32 v93, v89, v89
	v_max_f32_e32 v89, v94, v94
	v_mul_f32_e32 v94, v90, v90
	v_max_f32_e32 v90, v95, v95
	v_max_f32_e32 v91, v91, v91
	v_lshl_add_u64 v[96:97], s[16:17], 0, v[96:97]
	v_max_f32_e32 v92, 0, v92
	v_mul_f32_e32 v88, v88, v88
	v_max_f32_e32 v89, 0, v89
	v_max_f32_e32 v90, 0, v90
	v_max_f32_e32 v91, 0, v91
	v_max_f32_e32 v80, v80, v80
	v_lshl_add_u64 v[96:97], v[96:97], 0, v[148:149]
	v_mul_f32_e32 v92, v92, v92
	v_mul_f32_e32 v89, v89, v89
	v_mul_f32_e32 v90, v90, v90
	v_mul_f32_e32 v91, v91, v91
	v_cvt_pk_bf16_f32 v88, v92, v88
	v_max_f32_e32 v80, 0, v80
	v_max_f32_e32 v81, v81, v81
	v_max_f32_e32 v82, v82, v82
	v_cvt_pk_bf16_f32 v89, v89, v90
	v_cvt_pk_bf16_f32 v90, v98, v93
	v_cvt_pk_bf16_f32 v91, v94, v91
	global_store_dwordx4 v[96:97], v[88:91], off
	v_max_f32_e32 v81, 0, v81
	v_max_f32_e32 v82, 0, v82
	v_mul_f32_e32 v88, v80, v80
	v_max_f32_e32 v80, v85, v85
	v_max_f32_e32 v84, v84, v84
	v_max_f32_e32 v80, 0, v80
	v_mul_f32_e32 v85, v81, v81
	v_max_f32_e32 v81, v86, v86
	v_mul_f32_e32 v86, v82, v82
	v_max_f32_e32 v82, v87, v87
	v_max_f32_e32 v83, v83, v83
	v_max_f32_e32 v84, 0, v84
	v_mul_f32_e32 v80, v80, v80
	v_max_f32_e32 v81, 0, v81
	v_max_f32_e32 v82, 0, v82
	v_max_f32_e32 v83, 0, v83
	v_mul_f32_e32 v84, v84, v84
	v_mul_f32_e32 v81, v81, v81
	v_mul_f32_e32 v82, v82, v82
	v_mul_f32_e32 v83, v83, v83
	v_cvt_pk_bf16_f32 v80, v84, v80
	v_max_f32_e32 v72, v72, v72
	v_cvt_pk_bf16_f32 v81, v81, v82
	v_cvt_pk_bf16_f32 v82, v88, v85
	v_cvt_pk_bf16_f32 v83, v86, v83
	global_store_dwordx4 v[96:97], v[80:83], off offset:256
	v_max_f32_e32 v72, 0, v72
	v_max_f32_e32 v73, v73, v73
	v_or_b32_e32 v80, 48, v144
	v_max_f32_e32 v74, v74, v74
	v_ashrrev_i32_e32 v81, 31, v80
	v_mul_f32_e32 v82, v72, v72
	v_max_f32_e32 v72, v77, v77
	v_max_f32_e32 v73, 0, v73
	v_max_f32_e32 v74, 0, v74
	v_lshlrev_b64 v[80:81], 14, v[80:81]
	v_max_f32_e32 v76, v76, v76
	v_max_f32_e32 v72, 0, v72
	v_mul_f32_e32 v77, v73, v73
	v_max_f32_e32 v73, v78, v78
	v_mul_f32_e32 v78, v74, v74
	v_max_f32_e32 v74, v79, v79
	v_max_f32_e32 v75, v75, v75
	v_lshl_add_u64 v[80:81], s[16:17], 0, v[80:81]
	v_max_f32_e32 v76, 0, v76
	v_mul_f32_e32 v72, v72, v72
	v_max_f32_e32 v73, 0, v73
	v_max_f32_e32 v74, 0, v74
	v_max_f32_e32 v75, 0, v75
	v_max_f32_e32 v64, v64, v64
	v_max_f32_e32 v65, v65, v65
	v_max_f32_e32 v66, v66, v66
	v_lshl_add_u64 v[80:81], v[80:81], 0, v[148:149]
	v_mul_f32_e32 v76, v76, v76
	v_mul_f32_e32 v73, v73, v73
	v_mul_f32_e32 v74, v74, v74
	v_mul_f32_e32 v75, v75, v75
	v_cvt_pk_bf16_f32 v72, v76, v72
	v_max_f32_e32 v64, 0, v64
	v_max_f32_e32 v65, 0, v65
	v_max_f32_e32 v66, 0, v66
	v_cvt_pk_bf16_f32 v73, v73, v74
	v_cvt_pk_bf16_f32 v74, v82, v77
	v_cvt_pk_bf16_f32 v75, v78, v75
	global_store_dwordx4 v[80:81], v[72:75], off
	v_max_f32_e32 v68, v68, v68
	v_max_f32_e32 v67, v67, v67
	v_mul_f32_e32 v72, v64, v64
	v_max_f32_e32 v64, v69, v69
	v_mul_f32_e32 v69, v65, v65
	v_max_f32_e32 v65, v70, v70
	v_mul_f32_e32 v70, v66, v66
	v_max_f32_e32 v66, v71, v71
	v_max_f32_e32 v64, 0, v64
	v_max_f32_e32 v65, 0, v65
	v_max_f32_e32 v66, 0, v66
	v_max_f32_e32 v68, 0, v68
	v_mul_f32_e32 v64, v64, v64
	v_mul_f32_e32 v65, v65, v65
	v_max_f32_e32 v67, 0, v67
	v_mul_f32_e32 v66, v66, v66
	v_max_f32_e32 v56, v56, v56
	v_mul_f32_e32 v68, v68, v68
	v_mul_f32_e32 v67, v67, v67
	v_cvt_pk_bf16_f32 v64, v68, v64
	v_cvt_pk_bf16_f32 v65, v65, v66
	v_cvt_pk_bf16_f32 v66, v72, v69
	v_max_f32_e32 v56, 0, v56
	v_max_f32_e32 v57, v57, v57
	v_max_f32_e32 v58, v58, v58
	v_cvt_pk_bf16_f32 v67, v70, v67
	global_store_dwordx4 v[80:81], v[64:67], off offset:256
	v_max_f32_e32 v60, v60, v60
	v_max_f32_e32 v57, 0, v57
	v_mul_f32_e32 v66, v56, v56
	v_max_f32_e32 v56, v61, v61
	v_max_f32_e32 v58, 0, v58
	s_mov_b64 s[6:7], 0x200000
	v_max_f32_e32 v60, 0, v60
	v_max_f32_e32 v56, 0, v56
	v_mul_f32_e32 v61, v57, v57
	v_max_f32_e32 v57, v62, v62
	v_mul_f32_e32 v62, v58, v58
	v_max_f32_e32 v58, v63, v63
	v_lshl_add_u64 v[64:65], v[138:139], 0, s[6:7]
	v_mul_f32_e32 v60, v60, v60
	v_mul_f32_e32 v56, v56, v56
	v_max_f32_e32 v57, 0, v57
	v_max_f32_e32 v58, 0, v58
	v_max_f32_e32 v59, v59, v59
	s_mov_b32 s6, 0x200000
	v_mul_f32_e32 v57, v57, v57
	v_max_f32_e32 v59, 0, v59
	v_mul_f32_e32 v58, v58, v58
	v_cvt_pk_bf16_f32 v56, v60, v56
	v_add_co_u32_e32 v60, vcc, s6, v138
	v_max_f32_e32 v48, v48, v48
	v_max_f32_e32 v49, v49, v49
	v_max_f32_e32 v50, v50, v50
	v_mul_f32_e32 v59, v59, v59
	v_cvt_pk_bf16_f32 v57, v57, v58
	v_cvt_pk_bf16_f32 v58, v66, v61
	v_addc_co_u32_e32 v61, vcc, 0, v139, vcc
	v_max_f32_e32 v48, 0, v48
	v_max_f32_e32 v49, 0, v49
	v_max_f32_e32 v50, 0, v50
	v_cvt_pk_bf16_f32 v59, v62, v59
	global_store_dwordx4 v[60:61], v[56:59], off
	v_max_f32_e32 v52, v52, v52
	v_max_f32_e32 v51, v51, v51
	v_mul_f32_e32 v56, v48, v48
	v_max_f32_e32 v48, v53, v53
	v_mul_f32_e32 v53, v49, v49
	v_max_f32_e32 v49, v54, v54
	v_mul_f32_e32 v54, v50, v50
	v_max_f32_e32 v50, v55, v55
	v_max_f32_e32 v48, 0, v48
	v_max_f32_e32 v49, 0, v49
	v_max_f32_e32 v50, 0, v50
	v_max_f32_e32 v52, 0, v52
	v_mul_f32_e32 v48, v48, v48
	v_mul_f32_e32 v49, v49, v49
	v_max_f32_e32 v51, 0, v51
	v_mul_f32_e32 v50, v50, v50
	v_max_f32_e32 v40, v40, v40
	v_mul_f32_e32 v52, v52, v52
	v_mul_f32_e32 v51, v51, v51
	v_cvt_pk_bf16_f32 v48, v52, v48
	v_cvt_pk_bf16_f32 v49, v49, v50
	v_cvt_pk_bf16_f32 v50, v56, v53
	v_max_f32_e32 v40, 0, v40
	v_max_f32_e32 v41, v41, v41
	v_max_f32_e32 v42, v42, v42
	v_cvt_pk_bf16_f32 v51, v54, v51
	global_store_dwordx4 v[64:65], v[48:51], off offset:256
	v_max_f32_e32 v44, v44, v44
	v_max_f32_e32 v41, 0, v41
	v_mul_f32_e32 v50, v40, v40
	v_max_f32_e32 v40, v45, v45
	v_max_f32_e32 v42, 0, v42
	s_mov_b64 s[6:7], 0x240000
	v_max_f32_e32 v44, 0, v44
	v_max_f32_e32 v40, 0, v40
	v_mul_f32_e32 v45, v41, v41
	v_max_f32_e32 v41, v46, v46
	v_mul_f32_e32 v46, v42, v42
	v_max_f32_e32 v42, v47, v47
	v_lshl_add_u64 v[48:49], v[138:139], 0, s[6:7]
	v_mul_f32_e32 v44, v44, v44
	v_mul_f32_e32 v40, v40, v40
	v_max_f32_e32 v41, 0, v41
	v_max_f32_e32 v42, 0, v42
	v_max_f32_e32 v43, v43, v43
	s_mov_b32 s6, 0x240000
	v_mul_f32_e32 v41, v41, v41
	v_max_f32_e32 v43, 0, v43
	v_mul_f32_e32 v42, v42, v42
	v_cvt_pk_bf16_f32 v40, v44, v40
	v_add_co_u32_e32 v44, vcc, s6, v138
	v_max_f32_e32 v32, v32, v32
	v_max_f32_e32 v33, v33, v33
	v_max_f32_e32 v34, v34, v34
	v_mul_f32_e32 v43, v43, v43
	v_cvt_pk_bf16_f32 v41, v41, v42
	v_cvt_pk_bf16_f32 v42, v50, v45
	v_addc_co_u32_e32 v45, vcc, 0, v139, vcc
	v_max_f32_e32 v32, 0, v32
	v_max_f32_e32 v33, 0, v33
	v_max_f32_e32 v34, 0, v34
	v_cvt_pk_bf16_f32 v43, v46, v43
	global_store_dwordx4 v[44:45], v[40:43], off
	v_max_f32_e32 v36, v36, v36
	v_max_f32_e32 v35, v35, v35
	v_mul_f32_e32 v40, v32, v32
	v_max_f32_e32 v32, v37, v37
	v_mul_f32_e32 v37, v33, v33
	v_max_f32_e32 v33, v38, v38
	v_mul_f32_e32 v38, v34, v34
	v_max_f32_e32 v34, v39, v39
	v_max_f32_e32 v32, 0, v32
	v_max_f32_e32 v33, 0, v33
	v_max_f32_e32 v34, 0, v34
	v_max_f32_e32 v36, 0, v36
	v_mul_f32_e32 v32, v32, v32
	v_mul_f32_e32 v33, v33, v33
	v_max_f32_e32 v35, 0, v35
	v_mul_f32_e32 v34, v34, v34
	v_max_f32_e32 v24, v24, v24
	v_mul_f32_e32 v36, v36, v36
	v_mul_f32_e32 v35, v35, v35
	v_cvt_pk_bf16_f32 v32, v36, v32
	v_cvt_pk_bf16_f32 v33, v33, v34
	v_cvt_pk_bf16_f32 v34, v40, v37
	v_max_f32_e32 v24, 0, v24
	v_max_f32_e32 v25, v25, v25
	v_max_f32_e32 v26, v26, v26
	v_cvt_pk_bf16_f32 v35, v38, v35
	global_store_dwordx4 v[48:49], v[32:35], off offset:256
	v_max_f32_e32 v28, v28, v28
	v_max_f32_e32 v25, 0, v25
	v_mul_f32_e32 v34, v24, v24
	v_max_f32_e32 v24, v29, v29
	v_max_f32_e32 v26, 0, v26
	s_mov_b64 s[6:7], 0x280000
	v_max_f32_e32 v28, 0, v28
	v_max_f32_e32 v24, 0, v24
	v_mul_f32_e32 v29, v25, v25
	v_max_f32_e32 v25, v30, v30
	v_mul_f32_e32 v30, v26, v26
	v_max_f32_e32 v26, v31, v31
	v_lshl_add_u64 v[32:33], v[138:139], 0, s[6:7]
	v_mul_f32_e32 v28, v28, v28
	v_mul_f32_e32 v24, v24, v24
	v_max_f32_e32 v25, 0, v25
	v_max_f32_e32 v26, 0, v26
	v_max_f32_e32 v27, v27, v27
	s_mov_b32 s6, 0x280000
	v_mul_f32_e32 v25, v25, v25
	v_max_f32_e32 v27, 0, v27
	v_mul_f32_e32 v26, v26, v26
	v_cvt_pk_bf16_f32 v24, v28, v24
	v_add_co_u32_e32 v28, vcc, s6, v138
	v_max_f32_e32 v16, v16, v16
	v_max_f32_e32 v17, v17, v17
	v_max_f32_e32 v18, v18, v18
	v_mul_f32_e32 v27, v27, v27
	v_cvt_pk_bf16_f32 v25, v25, v26
	v_cvt_pk_bf16_f32 v26, v34, v29
	v_addc_co_u32_e32 v29, vcc, 0, v139, vcc
	v_max_f32_e32 v16, 0, v16
	v_max_f32_e32 v17, 0, v17
	v_max_f32_e32 v18, 0, v18
	v_cvt_pk_bf16_f32 v27, v30, v27
	global_store_dwordx4 v[28:29], v[24:27], off
	v_max_f32_e32 v20, v20, v20
	v_max_f32_e32 v19, v19, v19
	v_mul_f32_e32 v24, v16, v16
	v_max_f32_e32 v16, v21, v21
	v_mul_f32_e32 v21, v17, v17
	v_max_f32_e32 v17, v22, v22
	v_mul_f32_e32 v22, v18, v18
	v_max_f32_e32 v18, v23, v23
	v_max_f32_e32 v16, 0, v16
	v_max_f32_e32 v17, 0, v17
	v_max_f32_e32 v18, 0, v18
	v_max_f32_e32 v20, 0, v20
	v_mul_f32_e32 v16, v16, v16
	v_mul_f32_e32 v17, v17, v17
	v_max_f32_e32 v19, 0, v19
	v_mul_f32_e32 v18, v18, v18
	v_max_f32_e32 v8, v8, v8
	v_mul_f32_e32 v20, v20, v20
	v_mul_f32_e32 v19, v19, v19
	v_cvt_pk_bf16_f32 v16, v20, v16
	v_cvt_pk_bf16_f32 v17, v17, v18
	v_cvt_pk_bf16_f32 v18, v24, v21
	v_max_f32_e32 v8, 0, v8
	v_max_f32_e32 v9, v9, v9
	v_max_f32_e32 v10, v10, v10
	v_cvt_pk_bf16_f32 v19, v22, v19
	global_store_dwordx4 v[32:33], v[16:19], off offset:256
	v_max_f32_e32 v12, v12, v12
	v_max_f32_e32 v9, 0, v9
	v_mul_f32_e32 v18, v8, v8
	v_max_f32_e32 v8, v13, v13
	v_max_f32_e32 v10, 0, v10
	s_mov_b64 s[6:7], 0x2c0000
	v_max_f32_e32 v12, 0, v12
	v_max_f32_e32 v8, 0, v8
	v_mul_f32_e32 v13, v9, v9
	v_max_f32_e32 v9, v14, v14
	v_mul_f32_e32 v14, v10, v10
	v_max_f32_e32 v10, v15, v15
	v_lshl_add_u64 v[16:17], v[138:139], 0, s[6:7]
	v_mul_f32_e32 v12, v12, v12
	v_mul_f32_e32 v8, v8, v8
	v_max_f32_e32 v9, 0, v9
	v_max_f32_e32 v10, 0, v10
	v_max_f32_e32 v11, v11, v11
	s_mov_b32 s6, 0x2c0000
	v_mul_f32_e32 v9, v9, v9
	v_max_f32_e32 v11, 0, v11
	v_mul_f32_e32 v10, v10, v10
	v_cvt_pk_bf16_f32 v8, v12, v8
	v_add_co_u32_e32 v12, vcc, s6, v138
	v_max_f32_e32 v0, v0, v0
	v_max_f32_e32 v1, v1, v1
	v_max_f32_e32 v2, v2, v2
	v_mul_f32_e32 v11, v11, v11
	v_cvt_pk_bf16_f32 v9, v9, v10
	v_cvt_pk_bf16_f32 v10, v18, v13
	v_addc_co_u32_e32 v13, vcc, 0, v139, vcc
	v_max_f32_e32 v0, 0, v0
	v_max_f32_e32 v1, 0, v1
	v_max_f32_e32 v2, 0, v2
	v_cvt_pk_bf16_f32 v11, v14, v11
	global_store_dwordx4 v[12:13], v[8:11], off
	v_max_f32_e32 v3, v3, v3
	v_max_f32_e32 v4, v4, v4
	v_mul_f32_e32 v8, v0, v0
	v_max_f32_e32 v0, v5, v5
	v_mul_f32_e32 v5, v1, v1
	v_max_f32_e32 v1, v6, v6
	v_mul_f32_e32 v6, v2, v2
	v_max_f32_e32 v2, v7, v7
	v_max_f32_e32 v0, 0, v0
	v_max_f32_e32 v1, 0, v1
	v_max_f32_e32 v2, 0, v2
	v_max_f32_e32 v3, 0, v3
	v_max_f32_e32 v4, 0, v4
	v_mul_f32_e32 v0, v0, v0
	v_mul_f32_e32 v1, v1, v1
	v_mul_f32_e32 v2, v2, v2
	v_mul_f32_e32 v3, v3, v3
	s_and_b64 vcc, exec, s[38:39]
	s_mov_b32 s6, s24
	s_mov_b32 s7, s34
	s_mov_b64 s[22:23], s[44:45]
	s_mov_b64 s[20:21], s[42:43]
	v_mul_f32_e32 v4, v4, v4
	v_cvt_pk_bf16_f32 v0, v4, v0
	v_cvt_pk_bf16_f32 v1, v1, v2
	v_cvt_pk_bf16_f32 v2, v8, v5
	v_cvt_pk_bf16_f32 v3, v6, v3
	global_store_dwordx4 v[16:17], v[0:3], off offset:256
	s_cbranch_vccz .LBB0_770
	s_waitcnt vmcnt(0)
	v_readlane_b32 s34, v253, 45
	s_cmpk_gt_u32 s14, 0xff
	v_readlane_b32 s35, v253, 46
	s_cbranch_scc1 .LBB0_777
	s_barrier

.LBB0_835:
	s_ashr_i32 s17, s16, 31
	s_lshl_b64 s[6:7], s[16:17], 22
	s_add_u32 s24, s41, s6
	v_cmp_lt_i64_e32 vcc, s[14:15], v[160:161]
	s_addc_u32 s25, s43, s7
	s_ashr_i32 s1, s0, 31
	s_lshl_b64 s[14:15], s[0:1], 22
	s_add_u32 s14, s49, s14
	s_addc_u32 s15, s50, s15
	s_cmp_ge_u32 s2, 0x80
	s_cselect_b32 s100, 0x2000, 0
	s_cmp_eq_u32 s62, 1
	s_cselect_b32 s100, s100, 0
	s_cmp_lg_u32 s98, 0
	s_cselect_b32 s100, s100, 0
	s_add_u32 s24, s24, s100
	s_addc_u32 s25, s25, 0
	s_add_u32 s14, s14, s100
	s_addc_u32 s15, s15, 0
	s_and_b64 s[6:7], vcc, exec
	s_cselect_b32 s6, s25, s21
	s_cselect_b32 s7, s24, s20
	s_and_b64 s[34:35], vcc, exec
	s_cselect_b32 s1, s15, s23
	s_cselect_b32 s17, s14, s22
	s_cmp_lt_u32 s2, 0x80
	s_cselect_b32 s99, 1, 2
	s_cmp_eq_u32 s62, s99
	s_cselect_b32 s99, s99, 0
	s_cmp_lg_u32 s98, 0
	s_cselect_b32 s99, s99, 0
	s_add_u32 s20, s20, 0x200080
	s_addc_u32 s21, s21, 0
	s_add_u32 s63, s22, 0x100
	v_mov_b32_e32 v0, 0
	s_addc_u32 s68, s23, 0
	s_cmp_lg_u32 s99, 0
	s_cselect_b32 s69, 62, -2
	v_mov_b32_e32 v1, v0
	v_mov_b32_e32 v2, v0
	v_mov_b32_e32 v3, v0
	v_mov_b32_e32 v4, v0
	v_mov_b32_e32 v5, v0
	v_mov_b32_e32 v6, v0
	v_mov_b32_e32 v7, v0
	v_mov_b32_e32 v12, v0
	v_mov_b32_e32 v13, v0
	v_mov_b32_e32 v14, v0
	v_mov_b32_e32 v15, v0
	v_mov_b32_e32 v20, v0
	v_mov_b32_e32 v21, v0
	v_mov_b32_e32 v22, v0
	v_mov_b32_e32 v23, v0
	v_mov_b32_e32 v28, v0
	v_mov_b32_e32 v29, v0
	v_mov_b32_e32 v30, v0
	v_mov_b32_e32 v31, v0
	v_mov_b32_e32 v36, v0
	v_mov_b32_e32 v37, v0
	v_mov_b32_e32 v38, v0
	v_mov_b32_e32 v39, v0
	v_mov_b32_e32 v44, v0
	v_mov_b32_e32 v45, v0
	v_mov_b32_e32 v46, v0
	v_mov_b32_e32 v47, v0
	v_mov_b32_e32 v52, v0
	v_mov_b32_e32 v53, v0
	v_mov_b32_e32 v54, v0
	v_mov_b32_e32 v55, v0
	v_mov_b32_e32 v8, v0
	v_mov_b32_e32 v9, v0
	v_mov_b32_e32 v10, v0
	v_mov_b32_e32 v11, v0
	v_mov_b32_e32 v16, v0
	v_mov_b32_e32 v17, v0
	v_mov_b32_e32 v18, v0
	v_mov_b32_e32 v19, v0
	v_mov_b32_e32 v24, v0
	v_mov_b32_e32 v25, v0
	v_mov_b32_e32 v26, v0
	v_mov_b32_e32 v27, v0
	v_mov_b32_e32 v32, v0
	v_mov_b32_e32 v33, v0
	v_mov_b32_e32 v34, v0
	v_mov_b32_e32 v35, v0
	v_mov_b32_e32 v40, v0
	v_mov_b32_e32 v41, v0
	v_mov_b32_e32 v42, v0
	v_mov_b32_e32 v43, v0
	v_mov_b32_e32 v48, v0
	v_mov_b32_e32 v49, v0
	v_mov_b32_e32 v50, v0
	v_mov_b32_e32 v51, v0
	v_mov_b32_e32 v56, v0
	v_mov_b32_e32 v57, v0
	v_mov_b32_e32 v58, v0
	v_mov_b32_e32 v59, v0
	v_mov_b32_e32 v60, v0
	v_mov_b32_e32 v61, v0
	v_mov_b32_e32 v62, v0
	v_mov_b32_e32 v63, v0
	v_mov_b32_e32 v64, v0
	v_mov_b32_e32 v65, v0
	v_mov_b32_e32 v66, v0
	v_mov_b32_e32 v67, v0
	v_mov_b32_e32 v68, v0
	v_mov_b32_e32 v69, v0
	v_mov_b32_e32 v70, v0
	v_mov_b32_e32 v71, v0
	v_mov_b32_e32 v76, v0
	v_mov_b32_e32 v77, v0
	v_mov_b32_e32 v78, v0
	v_mov_b32_e32 v79, v0
	v_mov_b32_e32 v84, v0
	v_mov_b32_e32 v85, v0
	v_mov_b32_e32 v86, v0
	v_mov_b32_e32 v87, v0
	v_mov_b32_e32 v92, v0
	v_mov_b32_e32 v93, v0
	v_mov_b32_e32 v94, v0
	v_mov_b32_e32 v95, v0
	v_mov_b32_e32 v100, v0
	v_mov_b32_e32 v101, v0
	v_mov_b32_e32 v102, v0
	v_mov_b32_e32 v103, v0
	v_mov_b32_e32 v108, v0
	v_mov_b32_e32 v109, v0
	v_mov_b32_e32 v110, v0
	v_mov_b32_e32 v111, v0
	v_mov_b32_e32 v116, v0
	v_mov_b32_e32 v117, v0
	v_mov_b32_e32 v118, v0
	v_mov_b32_e32 v119, v0
	v_mov_b32_e32 v72, v0
	v_mov_b32_e32 v73, v0
	v_mov_b32_e32 v74, v0
	v_mov_b32_e32 v75, v0
	v_mov_b32_e32 v80, v0
	v_mov_b32_e32 v81, v0
	v_mov_b32_e32 v82, v0
	v_mov_b32_e32 v83, v0
	v_mov_b32_e32 v88, v0
	v_mov_b32_e32 v89, v0
	v_mov_b32_e32 v90, v0
	v_mov_b32_e32 v91, v0
	v_mov_b32_e32 v96, v0
	v_mov_b32_e32 v97, v0
	v_mov_b32_e32 v98, v0
	v_mov_b32_e32 v99, v0
	v_mov_b32_e32 v104, v0
	v_mov_b32_e32 v105, v0
	v_mov_b32_e32 v106, v0
	v_mov_b32_e32 v107, v0
	v_mov_b32_e32 v112, v0
	v_mov_b32_e32 v113, v0
	v_mov_b32_e32 v114, v0
	v_mov_b32_e32 v115, v0
	v_mov_b32_e32 v128, v0
	v_mov_b32_e32 v129, v0
	v_mov_b32_e32 v130, v0
	v_mov_b32_e32 v131, v0
	v_mov_b32_e32 v140, v0
	v_mov_b32_e32 v141, v0
	v_mov_b32_e32 v142, v0
	v_mov_b32_e32 v143, v0
	v_writelane_b32 v246, s98, 0
	v_writelane_b32 v246, s99, 1
	v_add_u32_e32 v248, 0x10000, v183
	v_add_u32_e32 v249, 0x14000, v183
	v_add_u32_e32 v250, 0x18000, v183
	v_add_u32_e32 v251, 0x1c000, v183
.LBB0_836:
	s_add_u32 s22, s20, 0xffe00080
	s_addc_u32 s23, s21, -1
	s_add_i32 s78, 0, 0x10000
	ds_read_b128 v[120:123], v248
	ds_read_b128 v[124:127], v248 offset:1024
	ds_read_b128 v[132:135], v248 offset:2048
	ds_read_b128 v[136:139], v248 offset:3072
	s_cmpk_eq_i32 s69, 0x7c
	s_cselect_b32 s35, s6, s23
	s_cselect_b32 s34, s7, s22
	s_cselect_b32 s23, s1, s68
	s_cselect_b32 s22, s17, s63
	s_add_i32 m0, s52, 0xc000
	ds_read_b128 v[186:189], v185
	ds_read_b128 v[190:193], v185 offset:1024
	ds_read_b128 v[206:209], v185 offset:2048
	ds_read_b128 v[210:213], v185 offset:3072
	ds_read_b128 v[214:217], v185 offset:4096
	ds_read_b128 v[218:221], v185 offset:5120
	ds_read_b128 v[222:225], v185 offset:6144
	ds_read_b128 v[226:229], v185 offset:7168
	global_load_lds_dwordx4 v176, s[20:21]
	s_add_i32 m0, s52, 0xe000
	s_nop 0
	global_load_lds_dwordx4 v178, s[20:21]
	s_waitcnt lgkmcnt(8)
	s_barrier
	s_waitcnt lgkmcnt(0)
	s_setprio 1
	s_waitcnt lgkmcnt(0)
	v_mfma_f32_16x16x32_bf16 v[140:143], v[120:123], v[186:189], v[140:143]
	v_mfma_f32_16x16x32_bf16 v[128:131], v[132:135], v[186:189], v[128:131]
	v_mfma_f32_16x16x32_bf16 v[112:115], v[120:123], v[206:209], v[112:115]
	v_mfma_f32_16x16x32_bf16 v[104:107], v[132:135], v[206:209], v[104:107]
	v_mfma_f32_16x16x32_bf16 v[96:99], v[120:123], v[214:217], v[96:99]
	v_mfma_f32_16x16x32_bf16 v[88:91], v[132:135], v[214:217], v[88:91]
	v_mfma_f32_16x16x32_bf16 v[80:83], v[120:123], v[222:225], v[80:83]
	v_mfma_f32_16x16x32_bf16 v[72:75], v[132:135], v[222:225], v[72:75]
	v_mfma_f32_16x16x32_bf16 v[140:143], v[124:127], v[190:193], v[140:143]
	v_mfma_f32_16x16x32_bf16 v[128:131], v[136:139], v[190:193], v[128:131]
	v_mfma_f32_16x16x32_bf16 v[112:115], v[124:127], v[210:213], v[112:115]
	v_mfma_f32_16x16x32_bf16 v[104:107], v[136:139], v[210:213], v[104:107]
	v_mfma_f32_16x16x32_bf16 v[96:99], v[124:127], v[218:221], v[96:99]
	v_mfma_f32_16x16x32_bf16 v[88:91], v[136:139], v[218:221], v[88:91]
	v_mfma_f32_16x16x32_bf16 v[80:83], v[124:127], v[226:229], v[80:83]
	v_mfma_f32_16x16x32_bf16 v[72:75], v[136:139], v[226:229], v[72:75]
	s_setprio 0
	s_barrier
	s_add_i32 s80, 0, 0x14000
	s_add_i32 s78, s78, s51
	ds_read_b128 v[230:233], v249
	ds_read_b128 v[234:237], v249 offset:1024
	ds_read_b128 v[238:241], v249 offset:2048
	ds_read_b128 v[242:245], v249 offset:3072
	s_mov_b32 m0, s78
	s_nop 0
	global_load_lds_dwordx4 v152, s[22:23]
	s_add_i32 m0, s78, 0x2000
	s_nop 0
	global_load_lds_dwordx4 v144, s[22:23]
	s_barrier
	s_waitcnt lgkmcnt(0)
	s_setprio 1
	s_waitcnt lgkmcnt(0)
	v_mfma_f32_16x16x32_bf16 v[116:119], v[230:233], v[186:189], v[116:119]
	v_mfma_f32_16x16x32_bf16 v[108:111], v[238:241], v[186:189], v[108:111]
	v_mfma_f32_16x16x32_bf16 v[100:103], v[230:233], v[206:209], v[100:103]
	v_mfma_f32_16x16x32_bf16 v[92:95], v[238:241], v[206:209], v[92:95]
	v_mfma_f32_16x16x32_bf16 v[84:87], v[230:233], v[214:217], v[84:87]
	v_mfma_f32_16x16x32_bf16 v[76:79], v[238:241], v[214:217], v[76:79]
	v_mfma_f32_16x16x32_bf16 v[68:71], v[230:233], v[222:225], v[68:71]
	v_mfma_f32_16x16x32_bf16 v[64:67], v[238:241], v[222:225], v[64:67]
	v_mfma_f32_16x16x32_bf16 v[116:119], v[234:237], v[190:193], v[116:119]
	v_mfma_f32_16x16x32_bf16 v[108:111], v[242:245], v[190:193], v[108:111]
	v_mfma_f32_16x16x32_bf16 v[100:103], v[234:237], v[210:213], v[100:103]
	v_mfma_f32_16x16x32_bf16 v[92:95], v[242:245], v[210:213], v[92:95]
	v_mfma_f32_16x16x32_bf16 v[84:87], v[234:237], v[218:221], v[84:87]
	v_mfma_f32_16x16x32_bf16 v[76:79], v[242:245], v[218:221], v[76:79]
	v_mfma_f32_16x16x32_bf16 v[68:71], v[234:237], v[226:229], v[68:71]
	v_mfma_f32_16x16x32_bf16 v[64:67], v[242:245], v[226:229], v[64:67]
	s_setprio 0
	s_mov_b32 m0, s52
	s_add_u32 s98, s34, 0x80
	s_addc_u32 s99, s35, 0
	s_barrier
	ds_read_b128 v[186:189], v185 offset:16384
	ds_read_b128 v[190:193], v185 offset:17408
	ds_read_b128 v[206:209], v185 offset:18432
	ds_read_b128 v[210:213], v185 offset:19456
	ds_read_b128 v[214:217], v185 offset:20480
	ds_read_b128 v[218:221], v185 offset:21504
	ds_read_b128 v[222:225], v185 offset:22528
	ds_read_b128 v[226:229], v185 offset:23552
	global_load_lds_dwordx4 v148, s[34:35]
	s_mov_b32 m0, s53
	s_nop 0
	global_load_lds_dwordx4 v146, s[34:35]
	s_barrier
	s_waitcnt lgkmcnt(0)
	s_setprio 1
	s_waitcnt lgkmcnt(0)
	v_mfma_f32_16x16x32_bf16 v[60:63], v[120:123], v[186:189], v[60:63]
	v_mfma_f32_16x16x32_bf16 v[56:59], v[132:135], v[186:189], v[56:59]
	v_mfma_f32_16x16x32_bf16 v[48:51], v[120:123], v[206:209], v[48:51]
	v_mfma_f32_16x16x32_bf16 v[40:43], v[132:135], v[206:209], v[40:43]
	v_mfma_f32_16x16x32_bf16 v[32:35], v[120:123], v[214:217], v[32:35]
	v_mfma_f32_16x16x32_bf16 v[24:27], v[132:135], v[214:217], v[24:27]
	v_mfma_f32_16x16x32_bf16 v[16:19], v[120:123], v[222:225], v[16:19]
	v_mfma_f32_16x16x32_bf16 v[8:11], v[132:135], v[222:225], v[8:11]
	v_mfma_f32_16x16x32_bf16 v[60:63], v[124:127], v[190:193], v[60:63]
	v_mfma_f32_16x16x32_bf16 v[56:59], v[136:139], v[190:193], v[56:59]
	v_mfma_f32_16x16x32_bf16 v[48:51], v[124:127], v[210:213], v[48:51]
	v_mfma_f32_16x16x32_bf16 v[40:43], v[136:139], v[210:213], v[40:43]
	v_mfma_f32_16x16x32_bf16 v[32:35], v[124:127], v[218:221], v[32:35]
	v_mfma_f32_16x16x32_bf16 v[24:27], v[136:139], v[218:221], v[24:27]
	v_mfma_f32_16x16x32_bf16 v[16:19], v[124:127], v[226:229], v[16:19]
	v_mfma_f32_16x16x32_bf16 v[8:11], v[136:139], v[226:229], v[8:11]
	s_setprio 0
	s_barrier
	s_add_u32 s78, s22, 0x200000
	s_addc_u32 s79, s23, 0
	s_add_i32 s80, s80, s51
	s_mov_b32 m0, s80
	s_nop 0
	global_load_lds_dwordx4 v152, s[78:79]
	s_add_i32 m0, s80, 0x2000
	s_nop 0
	global_load_lds_dwordx4 v144, s[78:79]
	s_waitcnt vmcnt(6)
	s_barrier
	s_setprio 1
	v_mfma_f32_16x16x32_bf16 v[52:55], v[230:233], v[186:189], v[52:55]
	v_mfma_f32_16x16x32_bf16 v[44:47], v[238:241], v[186:189], v[44:47]
	v_mfma_f32_16x16x32_bf16 v[36:39], v[230:233], v[206:209], v[36:39]
	v_mfma_f32_16x16x32_bf16 v[28:31], v[238:241], v[206:209], v[28:31]
	v_mfma_f32_16x16x32_bf16 v[20:23], v[230:233], v[214:217], v[20:23]
	v_mfma_f32_16x16x32_bf16 v[12:15], v[238:241], v[214:217], v[12:15]
	v_mfma_f32_16x16x32_bf16 v[4:7], v[230:233], v[222:225], v[4:7]
	v_mfma_f32_16x16x32_bf16 v[0:3], v[238:241], v[222:225], v[0:3]
	v_mfma_f32_16x16x32_bf16 v[52:55], v[234:237], v[190:193], v[52:55]
	v_mfma_f32_16x16x32_bf16 v[44:47], v[242:245], v[190:193], v[44:47]
	v_mfma_f32_16x16x32_bf16 v[36:39], v[234:237], v[210:213], v[36:39]
	v_mfma_f32_16x16x32_bf16 v[28:31], v[242:245], v[210:213], v[28:31]
	v_mfma_f32_16x16x32_bf16 v[20:23], v[234:237], v[218:221], v[20:23]
	v_mfma_f32_16x16x32_bf16 v[12:15], v[242:245], v[218:221], v[12:15]
	v_mfma_f32_16x16x32_bf16 v[4:7], v[234:237], v[226:229], v[4:7]
	v_mfma_f32_16x16x32_bf16 v[0:3], v[242:245], v[226:229], v[0:3]
	s_setprio 0
	s_add_i32 s78, 0, 0x18000
	s_barrier
	ds_read_b128 v[120:123], v250
	ds_read_b128 v[124:127], v250 offset:1024
	ds_read_b128 v[132:135], v250 offset:2048
	ds_read_b128 v[136:139], v250 offset:3072
	s_add_u32 s34, s34, 0x200000
	s_addc_u32 s35, s35, 0
	s_mov_b32 m0, s54
	ds_read_b128 v[186:189], v185 offset:32768
	ds_read_b128 v[190:193], v185 offset:33792
	ds_read_b128 v[206:209], v185 offset:34816
	ds_read_b128 v[210:213], v185 offset:35840
	ds_read_b128 v[214:217], v185 offset:36864
	ds_read_b128 v[218:221], v185 offset:37888
	ds_read_b128 v[222:225], v185 offset:38912
	ds_read_b128 v[226:229], v185 offset:39936
	global_load_lds_dwordx4 v148, s[34:35]
	s_mov_b32 m0, s55
	s_nop 0
	global_load_lds_dwordx4 v146, s[34:35]
	s_waitcnt lgkmcnt(8)
	s_barrier
	s_waitcnt lgkmcnt(0)
	s_setprio 1
	s_waitcnt lgkmcnt(0)
	v_mfma_f32_16x16x32_bf16 v[140:143], v[120:123], v[186:189], v[140:143]
	v_mfma_f32_16x16x32_bf16 v[128:131], v[132:135], v[186:189], v[128:131]
	v_mfma_f32_16x16x32_bf16 v[112:115], v[120:123], v[206:209], v[112:115]
	v_mfma_f32_16x16x32_bf16 v[104:107], v[132:135], v[206:209], v[104:107]
	v_mfma_f32_16x16x32_bf16 v[96:99], v[120:123], v[214:217], v[96:99]
	v_mfma_f32_16x16x32_bf16 v[88:91], v[132:135], v[214:217], v[88:91]
	v_mfma_f32_16x16x32_bf16 v[80:83], v[120:123], v[222:225], v[80:83]
	v_mfma_f32_16x16x32_bf16 v[72:75], v[132:135], v[222:225], v[72:75]
	v_mfma_f32_16x16x32_bf16 v[140:143], v[124:127], v[190:193], v[140:143]
	v_mfma_f32_16x16x32_bf16 v[128:131], v[136:139], v[190:193], v[128:131]
	v_mfma_f32_16x16x32_bf16 v[112:115], v[124:127], v[210:213], v[112:115]
	v_mfma_f32_16x16x32_bf16 v[104:107], v[136:139], v[210:213], v[104:107]
	v_mfma_f32_16x16x32_bf16 v[96:99], v[124:127], v[218:221], v[96:99]
	v_mfma_f32_16x16x32_bf16 v[88:91], v[136:139], v[218:221], v[88:91]
	v_mfma_f32_16x16x32_bf16 v[80:83], v[124:127], v[226:229], v[80:83]
	v_mfma_f32_16x16x32_bf16 v[72:75], v[136:139], v[226:229], v[72:75]
	s_setprio 0
	s_barrier
	s_add_i32 s34, 0, 0x1c000
	s_add_i32 s35, s78, s51
	s_add_u32 s100, s22, 0x80
	s_addc_u32 s101, s23, 0
	s_mov_b32 m0, s35
	ds_read_b128 v[230:233], v251
	ds_read_b128 v[234:237], v251 offset:1024
	ds_read_b128 v[238:241], v251 offset:2048
	ds_read_b128 v[242:245], v251 offset:3072
	global_load_lds_dwordx4 v152, s[100:101]
	s_add_i32 m0, s35, 0x2000
	s_nop 0
	global_load_lds_dwordx4 v144, s[100:101]
	s_barrier
	s_waitcnt lgkmcnt(0)
	s_setprio 1
	s_waitcnt lgkmcnt(0)
	v_mfma_f32_16x16x32_bf16 v[116:119], v[230:233], v[186:189], v[116:119]
	v_mfma_f32_16x16x32_bf16 v[108:111], v[238:241], v[186:189], v[108:111]
	v_mfma_f32_16x16x32_bf16 v[100:103], v[230:233], v[206:209], v[100:103]
	v_mfma_f32_16x16x32_bf16 v[92:95], v[238:241], v[206:209], v[92:95]
	v_mfma_f32_16x16x32_bf16 v[84:87], v[230:233], v[214:217], v[84:87]
	v_mfma_f32_16x16x32_bf16 v[76:79], v[238:241], v[214:217], v[76:79]
	v_mfma_f32_16x16x32_bf16 v[68:71], v[230:233], v[222:225], v[68:71]
	v_mfma_f32_16x16x32_bf16 v[64:67], v[238:241], v[222:225], v[64:67]
	v_mfma_f32_16x16x32_bf16 v[116:119], v[234:237], v[190:193], v[116:119]
	v_mfma_f32_16x16x32_bf16 v[108:111], v[242:245], v[190:193], v[108:111]
	v_mfma_f32_16x16x32_bf16 v[100:103], v[234:237], v[210:213], v[100:103]
	v_mfma_f32_16x16x32_bf16 v[92:95], v[242:245], v[210:213], v[92:95]
	v_mfma_f32_16x16x32_bf16 v[84:87], v[234:237], v[218:221], v[84:87]
	v_mfma_f32_16x16x32_bf16 v[76:79], v[242:245], v[218:221], v[76:79]
	v_mfma_f32_16x16x32_bf16 v[68:71], v[234:237], v[226:229], v[68:71]
	v_mfma_f32_16x16x32_bf16 v[64:67], v[242:245], v[226:229], v[64:67]
	s_setprio 0
	s_mov_b32 m0, s60
	s_barrier
	ds_read_b128 v[186:189], v185 offset:49152
	ds_read_b128 v[190:193], v185 offset:50176
	ds_read_b128 v[206:209], v185 offset:51200
	ds_read_b128 v[210:213], v185 offset:52224
	ds_read_b128 v[214:217], v185 offset:53248
	ds_read_b128 v[218:221], v185 offset:54272
	ds_read_b128 v[222:225], v185 offset:55296
	ds_read_b128 v[226:229], v185 offset:56320
	global_load_lds_dwordx4 v148, s[98:99]
	s_mov_b32 m0, s61
	s_nop 0
	global_load_lds_dwordx4 v146, s[98:99]
	s_barrier
	s_waitcnt lgkmcnt(0)
	s_setprio 1
	s_waitcnt lgkmcnt(0)
	v_mfma_f32_16x16x32_bf16 v[60:63], v[120:123], v[186:189], v[60:63]
	v_mfma_f32_16x16x32_bf16 v[56:59], v[132:135], v[186:189], v[56:59]
	v_mfma_f32_16x16x32_bf16 v[48:51], v[120:123], v[206:209], v[48:51]
	v_mfma_f32_16x16x32_bf16 v[40:43], v[132:135], v[206:209], v[40:43]
	v_mfma_f32_16x16x32_bf16 v[32:35], v[120:123], v[214:217], v[32:35]
	v_mfma_f32_16x16x32_bf16 v[24:27], v[132:135], v[214:217], v[24:27]
	v_mfma_f32_16x16x32_bf16 v[16:19], v[120:123], v[222:225], v[16:19]
	v_mfma_f32_16x16x32_bf16 v[8:11], v[132:135], v[222:225], v[8:11]
	v_mfma_f32_16x16x32_bf16 v[60:63], v[124:127], v[190:193], v[60:63]
	v_mfma_f32_16x16x32_bf16 v[56:59], v[136:139], v[190:193], v[56:59]
	v_mfma_f32_16x16x32_bf16 v[48:51], v[124:127], v[210:213], v[48:51]
	v_mfma_f32_16x16x32_bf16 v[40:43], v[136:139], v[210:213], v[40:43]
	v_mfma_f32_16x16x32_bf16 v[32:35], v[124:127], v[218:221], v[32:35]
	v_mfma_f32_16x16x32_bf16 v[24:27], v[136:139], v[218:221], v[24:27]
	v_mfma_f32_16x16x32_bf16 v[16:19], v[124:127], v[226:229], v[16:19]
	v_mfma_f32_16x16x32_bf16 v[8:11], v[136:139], v[226:229], v[8:11]
	s_setprio 0
	s_barrier
	s_add_u32 s22, s22, 0x200080
	s_addc_u32 s23, s23, 0
	s_add_i32 s34, s34, s51
	s_mov_b32 m0, s34
	s_nop 0
	global_load_lds_dwordx4 v152, s[22:23]
	s_add_i32 m0, s34, 0x2000
	s_nop 0
	global_load_lds_dwordx4 v144, s[22:23]
	s_waitcnt vmcnt(6)
	s_barrier
	s_setprio 1
	v_mfma_f32_16x16x32_bf16 v[52:55], v[230:233], v[186:189], v[52:55]
	v_mfma_f32_16x16x32_bf16 v[44:47], v[238:241], v[186:189], v[44:47]
	v_mfma_f32_16x16x32_bf16 v[36:39], v[230:233], v[206:209], v[36:39]
	v_mfma_f32_16x16x32_bf16 v[28:31], v[238:241], v[206:209], v[28:31]
	v_mfma_f32_16x16x32_bf16 v[20:23], v[230:233], v[214:217], v[20:23]
	v_mfma_f32_16x16x32_bf16 v[12:15], v[238:241], v[214:217], v[12:15]
	v_mfma_f32_16x16x32_bf16 v[4:7], v[230:233], v[222:225], v[4:7]
	v_mfma_f32_16x16x32_bf16 v[0:3], v[238:241], v[222:225], v[0:3]
	v_mfma_f32_16x16x32_bf16 v[52:55], v[234:237], v[190:193], v[52:55]
	v_mfma_f32_16x16x32_bf16 v[44:47], v[242:245], v[190:193], v[44:47]
	v_mfma_f32_16x16x32_bf16 v[36:39], v[234:237], v[210:213], v[36:39]
	v_mfma_f32_16x16x32_bf16 v[28:31], v[242:245], v[210:213], v[28:31]
	v_mfma_f32_16x16x32_bf16 v[20:23], v[234:237], v[218:221], v[20:23]
	v_mfma_f32_16x16x32_bf16 v[12:15], v[242:245], v[218:221], v[12:15]
	v_mfma_f32_16x16x32_bf16 v[4:7], v[234:237], v[226:229], v[4:7]
	v_mfma_f32_16x16x32_bf16 v[0:3], v[242:245], v[226:229], v[0:3]
	s_setprio 0
	s_add_i32 s69, s69, 2
	s_add_u32 s20, s20, 0x100
	s_addc_u32 s21, s21, 0
	s_add_u32 s63, s63, 0x100
	s_addc_u32 s68, s68, 0
	s_cmpk_gt_u32 s69, 0x7d
	s_barrier
	s_cbranch_scc0 .LBB0_836
	v_readlane_b32 s98, v246, 0
	v_readlane_b32 s99, v246, 1
	s_cmp_eq_u32 s99, 0
	s_cbranch_scc1 .Lm2_epi
	s_and_b32 s100, s2, 0x7f
	s_lshl_b32 s100, s100, 18
	s_add_u32 s100, s100, 0x29800000
	s_add_u32 s100, s46, s100
	s_addc_u32 s101, s47, 0
	v_lshlrev_b32_e32 v186, 4, v182
	s_cmp_eq_u32 s99, 1
	s_cbranch_scc1 .Lm2_put_partial
	s_and_b32 s6, s2, 0x7f
	s_lshl_b32 s6, s6, 6
	s_add_u32 s6, s6, 0x2970a000
	s_add_u32 s6, s46, s6
	s_addc_u32 s7, s47, 0
	v_mov_b32_e32 v187, 0
	s_mov_b32 s99, 0
